# k7 + prologue: silu(c) loads batched (32 in flight), adaLN k-loop software-pipelined 16 row loads in flight
# speedup vs baseline: 1.0049x; 1.0049x over previous
.LBB0_7:
	s_mov_b64 s[0:1], 0x1000
	global_load_dword v116, v[2:3], off
	global_load_dword v117, v[2:3], off offset:2048
	v_lshl_add_u64 v[2:3], v[2:3], 0, s[0:1]
	global_load_dword v118, v[2:3], off
	global_load_dword v119, v[2:3], off offset:2048
	v_lshl_add_u64 v[2:3], v[2:3], 0, s[0:1]
	global_load_dword v120, v[2:3], off
	global_load_dword v121, v[2:3], off offset:2048
	v_lshl_add_u64 v[2:3], v[2:3], 0, s[0:1]
	global_load_dword v122, v[2:3], off
	global_load_dword v123, v[2:3], off offset:2048
	v_lshl_add_u64 v[2:3], v[2:3], 0, s[0:1]
	global_load_dword v124, v[2:3], off
	global_load_dword v125, v[2:3], off offset:2048
	v_lshl_add_u64 v[2:3], v[2:3], 0, s[0:1]
	global_load_dword v126, v[2:3], off
	global_load_dword v127, v[2:3], off offset:2048
	v_lshl_add_u64 v[2:3], v[2:3], 0, s[0:1]
	global_load_dword v128, v[2:3], off
	global_load_dword v129, v[2:3], off offset:2048
	v_lshl_add_u64 v[2:3], v[2:3], 0, s[0:1]
	global_load_dword v130, v[2:3], off
	global_load_dword v131, v[2:3], off offset:2048
	v_lshl_add_u64 v[2:3], v[2:3], 0, s[0:1]
	global_load_dword v132, v[2:3], off
	global_load_dword v133, v[2:3], off offset:2048
	v_lshl_add_u64 v[2:3], v[2:3], 0, s[0:1]
	global_load_dword v134, v[2:3], off
	global_load_dword v135, v[2:3], off offset:2048
	v_lshl_add_u64 v[2:3], v[2:3], 0, s[0:1]
	global_load_dword v136, v[2:3], off
	global_load_dword v137, v[2:3], off offset:2048
	v_lshl_add_u64 v[2:3], v[2:3], 0, s[0:1]
	global_load_dword v138, v[2:3], off
	global_load_dword v139, v[2:3], off offset:2048
	v_lshl_add_u64 v[2:3], v[2:3], 0, s[0:1]
	global_load_dword v140, v[2:3], off
	global_load_dword v141, v[2:3], off offset:2048
	v_lshl_add_u64 v[2:3], v[2:3], 0, s[0:1]
	global_load_dword v142, v[2:3], off
	global_load_dword v143, v[2:3], off offset:2048
	v_lshl_add_u64 v[2:3], v[2:3], 0, s[0:1]
	global_load_dword v144, v[2:3], off
	global_load_dword v145, v[2:3], off offset:2048
	v_lshl_add_u64 v[2:3], v[2:3], 0, s[0:1]
	global_load_dword v146, v[2:3], off
	global_load_dword v147, v[2:3], off offset:2048
	s_waitcnt vmcnt(31)
	v_mul_f32_e32 v7, 0xbfb8aa3b, v116
	v_exp_f32_e32 v7, v7
	s_nop 0
	v_add_f32_e32 v7, 1.0, v7
	v_div_scale_f32 v8, s[8:9], v7, v7, v116
	v_rcp_f32_e32 v9, v8
	v_div_scale_f32 v10, vcc, v116, v7, v116
	v_fma_f32 v11, -v8, v9, 1.0
	v_fmac_f32_e32 v9, v11, v9
	v_mul_f32_e32 v11, v10, v9
	v_fma_f32 v12, -v8, v11, v10
	v_fmac_f32_e32 v11, v12, v9
	v_fma_f32 v8, -v8, v11, v10
	v_div_fmas_f32 v8, v8, v9, v11
	v_div_fixup_f32 v116, v8, v7, v116
	ds_write_b32 v5, v116
	s_waitcnt vmcnt(30)
	v_mul_f32_e32 v7, 0xbfb8aa3b, v117
	v_exp_f32_e32 v7, v7
	s_nop 0
	v_add_f32_e32 v7, 1.0, v7
	v_div_scale_f32 v8, s[8:9], v7, v7, v117
	v_rcp_f32_e32 v9, v8
	v_div_scale_f32 v10, vcc, v117, v7, v117
	v_fma_f32 v11, -v8, v9, 1.0
	v_fmac_f32_e32 v9, v11, v9
	v_mul_f32_e32 v11, v10, v9
	v_fma_f32 v12, -v8, v11, v10
	v_fmac_f32_e32 v11, v12, v9
	v_fma_f32 v8, -v8, v11, v10
	v_div_fmas_f32 v8, v8, v9, v11
	v_div_fixup_f32 v117, v8, v7, v117
	ds_write_b32 v5, v117 offset:2048
	s_waitcnt vmcnt(29)
	v_mul_f32_e32 v7, 0xbfb8aa3b, v118
	v_exp_f32_e32 v7, v7
	s_nop 0
	v_add_f32_e32 v7, 1.0, v7
	v_div_scale_f32 v8, s[8:9], v7, v7, v118
	v_rcp_f32_e32 v9, v8
	v_div_scale_f32 v10, vcc, v118, v7, v118
	v_fma_f32 v11, -v8, v9, 1.0
	v_fmac_f32_e32 v9, v11, v9
	v_mul_f32_e32 v11, v10, v9
	v_fma_f32 v12, -v8, v11, v10
	v_fmac_f32_e32 v11, v12, v9
	v_fma_f32 v8, -v8, v11, v10
	v_div_fmas_f32 v8, v8, v9, v11
	v_div_fixup_f32 v118, v8, v7, v118
	ds_write_b32 v5, v118 offset:4096
	s_waitcnt vmcnt(28)
	v_mul_f32_e32 v7, 0xbfb8aa3b, v119
	v_exp_f32_e32 v7, v7
	s_nop 0
	v_add_f32_e32 v7, 1.0, v7
	v_div_scale_f32 v8, s[8:9], v7, v7, v119
	v_rcp_f32_e32 v9, v8
	v_div_scale_f32 v10, vcc, v119, v7, v119
	v_fma_f32 v11, -v8, v9, 1.0
	v_fmac_f32_e32 v9, v11, v9
	v_mul_f32_e32 v11, v10, v9
	v_fma_f32 v12, -v8, v11, v10
	v_fmac_f32_e32 v11, v12, v9
	v_fma_f32 v8, -v8, v11, v10
	v_div_fmas_f32 v8, v8, v9, v11
	v_div_fixup_f32 v119, v8, v7, v119
	ds_write_b32 v5, v119 offset:6144
	s_waitcnt vmcnt(27)
	v_mul_f32_e32 v7, 0xbfb8aa3b, v120
	v_exp_f32_e32 v7, v7
	s_nop 0
	v_add_f32_e32 v7, 1.0, v7
	v_div_scale_f32 v8, s[8:9], v7, v7, v120
	v_rcp_f32_e32 v9, v8
	v_div_scale_f32 v10, vcc, v120, v7, v120
	v_fma_f32 v11, -v8, v9, 1.0
	v_fmac_f32_e32 v9, v11, v9
	v_mul_f32_e32 v11, v10, v9
	v_fma_f32 v12, -v8, v11, v10
	v_fmac_f32_e32 v11, v12, v9
	v_fma_f32 v8, -v8, v11, v10
	v_div_fmas_f32 v8, v8, v9, v11
	v_div_fixup_f32 v120, v8, v7, v120
	ds_write_b32 v5, v120 offset:8192
	s_waitcnt vmcnt(26)
	v_mul_f32_e32 v7, 0xbfb8aa3b, v121
	v_exp_f32_e32 v7, v7
	s_nop 0
	v_add_f32_e32 v7, 1.0, v7
	v_div_scale_f32 v8, s[8:9], v7, v7, v121
	v_rcp_f32_e32 v9, v8
	v_div_scale_f32 v10, vcc, v121, v7, v121
	v_fma_f32 v11, -v8, v9, 1.0
	v_fmac_f32_e32 v9, v11, v9
	v_mul_f32_e32 v11, v10, v9
	v_fma_f32 v12, -v8, v11, v10
	v_fmac_f32_e32 v11, v12, v9
	v_fma_f32 v8, -v8, v11, v10
	v_div_fmas_f32 v8, v8, v9, v11
	v_div_fixup_f32 v121, v8, v7, v121
	ds_write_b32 v5, v121 offset:10240
	s_waitcnt vmcnt(25)
	v_mul_f32_e32 v7, 0xbfb8aa3b, v122
	v_exp_f32_e32 v7, v7
	s_nop 0
	v_add_f32_e32 v7, 1.0, v7
	v_div_scale_f32 v8, s[8:9], v7, v7, v122
	v_rcp_f32_e32 v9, v8
	v_div_scale_f32 v10, vcc, v122, v7, v122
	v_fma_f32 v11, -v8, v9, 1.0
	v_fmac_f32_e32 v9, v11, v9
	v_mul_f32_e32 v11, v10, v9
	v_fma_f32 v12, -v8, v11, v10
	v_fmac_f32_e32 v11, v12, v9
	v_fma_f32 v8, -v8, v11, v10
	v_div_fmas_f32 v8, v8, v9, v11
	v_div_fixup_f32 v122, v8, v7, v122
	ds_write_b32 v5, v122 offset:12288
	s_waitcnt vmcnt(24)
	v_mul_f32_e32 v7, 0xbfb8aa3b, v123
	v_exp_f32_e32 v7, v7
	s_nop 0
	v_add_f32_e32 v7, 1.0, v7
	v_div_scale_f32 v8, s[8:9], v7, v7, v123
	v_rcp_f32_e32 v9, v8
	v_div_scale_f32 v10, vcc, v123, v7, v123
	v_fma_f32 v11, -v8, v9, 1.0
	v_fmac_f32_e32 v9, v11, v9
	v_mul_f32_e32 v11, v10, v9
	v_fma_f32 v12, -v8, v11, v10
	v_fmac_f32_e32 v11, v12, v9
	v_fma_f32 v8, -v8, v11, v10
	v_div_fmas_f32 v8, v8, v9, v11
	v_div_fixup_f32 v123, v8, v7, v123
	ds_write_b32 v5, v123 offset:14336
	s_waitcnt vmcnt(23)
	v_mul_f32_e32 v7, 0xbfb8aa3b, v124
	v_exp_f32_e32 v7, v7
	s_nop 0
	v_add_f32_e32 v7, 1.0, v7
	v_div_scale_f32 v8, s[8:9], v7, v7, v124
	v_rcp_f32_e32 v9, v8
	v_div_scale_f32 v10, vcc, v124, v7, v124
	v_fma_f32 v11, -v8, v9, 1.0
	v_fmac_f32_e32 v9, v11, v9
	v_mul_f32_e32 v11, v10, v9
	v_fma_f32 v12, -v8, v11, v10
	v_fmac_f32_e32 v11, v12, v9
	v_fma_f32 v8, -v8, v11, v10
	v_div_fmas_f32 v8, v8, v9, v11
	v_div_fixup_f32 v124, v8, v7, v124
	ds_write_b32 v5, v124 offset:16384
	s_waitcnt vmcnt(22)
	v_mul_f32_e32 v7, 0xbfb8aa3b, v125
	v_exp_f32_e32 v7, v7
	s_nop 0
	v_add_f32_e32 v7, 1.0, v7
	v_div_scale_f32 v8, s[8:9], v7, v7, v125
	v_rcp_f32_e32 v9, v8
	v_div_scale_f32 v10, vcc, v125, v7, v125
	v_fma_f32 v11, -v8, v9, 1.0
	v_fmac_f32_e32 v9, v11, v9
	v_mul_f32_e32 v11, v10, v9
	v_fma_f32 v12, -v8, v11, v10
	v_fmac_f32_e32 v11, v12, v9
	v_fma_f32 v8, -v8, v11, v10
	v_div_fmas_f32 v8, v8, v9, v11
	v_div_fixup_f32 v125, v8, v7, v125
	ds_write_b32 v5, v125 offset:18432
	s_waitcnt vmcnt(21)
	v_mul_f32_e32 v7, 0xbfb8aa3b, v126
	v_exp_f32_e32 v7, v7
	s_nop 0
	v_add_f32_e32 v7, 1.0, v7
	v_div_scale_f32 v8, s[8:9], v7, v7, v126
	v_rcp_f32_e32 v9, v8
	v_div_scale_f32 v10, vcc, v126, v7, v126
	v_fma_f32 v11, -v8, v9, 1.0
	v_fmac_f32_e32 v9, v11, v9
	v_mul_f32_e32 v11, v10, v9
	v_fma_f32 v12, -v8, v11, v10
	v_fmac_f32_e32 v11, v12, v9
	v_fma_f32 v8, -v8, v11, v10
	v_div_fmas_f32 v8, v8, v9, v11
	v_div_fixup_f32 v126, v8, v7, v126
	ds_write_b32 v5, v126 offset:20480
	s_waitcnt vmcnt(20)
	v_mul_f32_e32 v7, 0xbfb8aa3b, v127
	v_exp_f32_e32 v7, v7
	s_nop 0
	v_add_f32_e32 v7, 1.0, v7
	v_div_scale_f32 v8, s[8:9], v7, v7, v127
	v_rcp_f32_e32 v9, v8
	v_div_scale_f32 v10, vcc, v127, v7, v127
	v_fma_f32 v11, -v8, v9, 1.0
	v_fmac_f32_e32 v9, v11, v9
	v_mul_f32_e32 v11, v10, v9
	v_fma_f32 v12, -v8, v11, v10
	v_fmac_f32_e32 v11, v12, v9
	v_fma_f32 v8, -v8, v11, v10
	v_div_fmas_f32 v8, v8, v9, v11
	v_div_fixup_f32 v127, v8, v7, v127
	ds_write_b32 v5, v127 offset:22528
	s_waitcnt vmcnt(19)
	v_mul_f32_e32 v7, 0xbfb8aa3b, v128
	v_exp_f32_e32 v7, v7
	s_nop 0
	v_add_f32_e32 v7, 1.0, v7
	v_div_scale_f32 v8, s[8:9], v7, v7, v128
	v_rcp_f32_e32 v9, v8
	v_div_scale_f32 v10, vcc, v128, v7, v128
	v_fma_f32 v11, -v8, v9, 1.0
	v_fmac_f32_e32 v9, v11, v9
	v_mul_f32_e32 v11, v10, v9
	v_fma_f32 v12, -v8, v11, v10
	v_fmac_f32_e32 v11, v12, v9
	v_fma_f32 v8, -v8, v11, v10
	v_div_fmas_f32 v8, v8, v9, v11
	v_div_fixup_f32 v128, v8, v7, v128
	ds_write_b32 v5, v128 offset:24576
	s_waitcnt vmcnt(18)
	v_mul_f32_e32 v7, 0xbfb8aa3b, v129
	v_exp_f32_e32 v7, v7
	s_nop 0
	v_add_f32_e32 v7, 1.0, v7
	v_div_scale_f32 v8, s[8:9], v7, v7, v129
	v_rcp_f32_e32 v9, v8
	v_div_scale_f32 v10, vcc, v129, v7, v129
	v_fma_f32 v11, -v8, v9, 1.0
	v_fmac_f32_e32 v9, v11, v9
	v_mul_f32_e32 v11, v10, v9
	v_fma_f32 v12, -v8, v11, v10
	v_fmac_f32_e32 v11, v12, v9
	v_fma_f32 v8, -v8, v11, v10
	v_div_fmas_f32 v8, v8, v9, v11
	v_div_fixup_f32 v129, v8, v7, v129
	ds_write_b32 v5, v129 offset:26624
	s_waitcnt vmcnt(17)
	v_mul_f32_e32 v7, 0xbfb8aa3b, v130
	v_exp_f32_e32 v7, v7
	s_nop 0
	v_add_f32_e32 v7, 1.0, v7
	v_div_scale_f32 v8, s[8:9], v7, v7, v130
	v_rcp_f32_e32 v9, v8
	v_div_scale_f32 v10, vcc, v130, v7, v130
	v_fma_f32 v11, -v8, v9, 1.0
	v_fmac_f32_e32 v9, v11, v9
	v_mul_f32_e32 v11, v10, v9
	v_fma_f32 v12, -v8, v11, v10
	v_fmac_f32_e32 v11, v12, v9
	v_fma_f32 v8, -v8, v11, v10
	v_div_fmas_f32 v8, v8, v9, v11
	v_div_fixup_f32 v130, v8, v7, v130
	ds_write_b32 v5, v130 offset:28672
	s_waitcnt vmcnt(16)
	v_mul_f32_e32 v7, 0xbfb8aa3b, v131
	v_exp_f32_e32 v7, v7
	s_nop 0
	v_add_f32_e32 v7, 1.0, v7
	v_div_scale_f32 v8, s[8:9], v7, v7, v131
	v_rcp_f32_e32 v9, v8
	v_div_scale_f32 v10, vcc, v131, v7, v131
	v_fma_f32 v11, -v8, v9, 1.0
	v_fmac_f32_e32 v9, v11, v9
	v_mul_f32_e32 v11, v10, v9
	v_fma_f32 v12, -v8, v11, v10
	v_fmac_f32_e32 v11, v12, v9
	v_fma_f32 v8, -v8, v11, v10
	v_div_fmas_f32 v8, v8, v9, v11
	v_div_fixup_f32 v131, v8, v7, v131
	ds_write_b32 v5, v131 offset:30720
	s_waitcnt vmcnt(15)
	v_mul_f32_e32 v7, 0xbfb8aa3b, v132
	v_exp_f32_e32 v7, v7
	s_nop 0
	v_add_f32_e32 v7, 1.0, v7
	v_div_scale_f32 v8, s[8:9], v7, v7, v132
	v_rcp_f32_e32 v9, v8
	v_div_scale_f32 v10, vcc, v132, v7, v132
	v_fma_f32 v11, -v8, v9, 1.0
	v_fmac_f32_e32 v9, v11, v9
	v_mul_f32_e32 v11, v10, v9
	v_fma_f32 v12, -v8, v11, v10
	v_fmac_f32_e32 v11, v12, v9
	v_fma_f32 v8, -v8, v11, v10
	v_div_fmas_f32 v8, v8, v9, v11
	v_div_fixup_f32 v132, v8, v7, v132
	ds_write_b32 v5, v132 offset:32768
	s_waitcnt vmcnt(14)
	v_mul_f32_e32 v7, 0xbfb8aa3b, v133
	v_exp_f32_e32 v7, v7
	s_nop 0
	v_add_f32_e32 v7, 1.0, v7
	v_div_scale_f32 v8, s[8:9], v7, v7, v133
	v_rcp_f32_e32 v9, v8
	v_div_scale_f32 v10, vcc, v133, v7, v133
	v_fma_f32 v11, -v8, v9, 1.0
	v_fmac_f32_e32 v9, v11, v9
	v_mul_f32_e32 v11, v10, v9
	v_fma_f32 v12, -v8, v11, v10
	v_fmac_f32_e32 v11, v12, v9
	v_fma_f32 v8, -v8, v11, v10
	v_div_fmas_f32 v8, v8, v9, v11
	v_div_fixup_f32 v133, v8, v7, v133
	ds_write_b32 v5, v133 offset:34816
	s_waitcnt vmcnt(13)
	v_mul_f32_e32 v7, 0xbfb8aa3b, v134
	v_exp_f32_e32 v7, v7
	s_nop 0
	v_add_f32_e32 v7, 1.0, v7
	v_div_scale_f32 v8, s[8:9], v7, v7, v134
	v_rcp_f32_e32 v9, v8
	v_div_scale_f32 v10, vcc, v134, v7, v134
	v_fma_f32 v11, -v8, v9, 1.0
	v_fmac_f32_e32 v9, v11, v9
	v_mul_f32_e32 v11, v10, v9
	v_fma_f32 v12, -v8, v11, v10
	v_fmac_f32_e32 v11, v12, v9
	v_fma_f32 v8, -v8, v11, v10
	v_div_fmas_f32 v8, v8, v9, v11
	v_div_fixup_f32 v134, v8, v7, v134
	ds_write_b32 v5, v134 offset:36864
	s_waitcnt vmcnt(12)
	v_mul_f32_e32 v7, 0xbfb8aa3b, v135
	v_exp_f32_e32 v7, v7
	s_nop 0
	v_add_f32_e32 v7, 1.0, v7
	v_div_scale_f32 v8, s[8:9], v7, v7, v135
	v_rcp_f32_e32 v9, v8
	v_div_scale_f32 v10, vcc, v135, v7, v135
	v_fma_f32 v11, -v8, v9, 1.0
	v_fmac_f32_e32 v9, v11, v9
	v_mul_f32_e32 v11, v10, v9
	v_fma_f32 v12, -v8, v11, v10
	v_fmac_f32_e32 v11, v12, v9
	v_fma_f32 v8, -v8, v11, v10
	v_div_fmas_f32 v8, v8, v9, v11
	v_div_fixup_f32 v135, v8, v7, v135
	ds_write_b32 v5, v135 offset:38912
	s_waitcnt vmcnt(11)
	v_mul_f32_e32 v7, 0xbfb8aa3b, v136
	v_exp_f32_e32 v7, v7
	s_nop 0
	v_add_f32_e32 v7, 1.0, v7
	v_div_scale_f32 v8, s[8:9], v7, v7, v136
	v_rcp_f32_e32 v9, v8
	v_div_scale_f32 v10, vcc, v136, v7, v136
	v_fma_f32 v11, -v8, v9, 1.0
	v_fmac_f32_e32 v9, v11, v9
	v_mul_f32_e32 v11, v10, v9
	v_fma_f32 v12, -v8, v11, v10
	v_fmac_f32_e32 v11, v12, v9
	v_fma_f32 v8, -v8, v11, v10
	v_div_fmas_f32 v8, v8, v9, v11
	v_div_fixup_f32 v136, v8, v7, v136
	ds_write_b32 v5, v136 offset:40960
	s_waitcnt vmcnt(10)
	v_mul_f32_e32 v7, 0xbfb8aa3b, v137
	v_exp_f32_e32 v7, v7
	s_nop 0
	v_add_f32_e32 v7, 1.0, v7
	v_div_scale_f32 v8, s[8:9], v7, v7, v137
	v_rcp_f32_e32 v9, v8
	v_div_scale_f32 v10, vcc, v137, v7, v137
	v_fma_f32 v11, -v8, v9, 1.0
	v_fmac_f32_e32 v9, v11, v9
	v_mul_f32_e32 v11, v10, v9
	v_fma_f32 v12, -v8, v11, v10
	v_fmac_f32_e32 v11, v12, v9
	v_fma_f32 v8, -v8, v11, v10
	v_div_fmas_f32 v8, v8, v9, v11
	v_div_fixup_f32 v137, v8, v7, v137
	ds_write_b32 v5, v137 offset:43008
	s_waitcnt vmcnt(9)
	v_mul_f32_e32 v7, 0xbfb8aa3b, v138
	v_exp_f32_e32 v7, v7
	s_nop 0
	v_add_f32_e32 v7, 1.0, v7
	v_div_scale_f32 v8, s[8:9], v7, v7, v138
	v_rcp_f32_e32 v9, v8
	v_div_scale_f32 v10, vcc, v138, v7, v138
	v_fma_f32 v11, -v8, v9, 1.0
	v_fmac_f32_e32 v9, v11, v9
	v_mul_f32_e32 v11, v10, v9
	v_fma_f32 v12, -v8, v11, v10
	v_fmac_f32_e32 v11, v12, v9
	v_fma_f32 v8, -v8, v11, v10
	v_div_fmas_f32 v8, v8, v9, v11
	v_div_fixup_f32 v138, v8, v7, v138
	ds_write_b32 v5, v138 offset:45056
	s_waitcnt vmcnt(8)
	v_mul_f32_e32 v7, 0xbfb8aa3b, v139
	v_exp_f32_e32 v7, v7
	s_nop 0
	v_add_f32_e32 v7, 1.0, v7
	v_div_scale_f32 v8, s[8:9], v7, v7, v139
	v_rcp_f32_e32 v9, v8
	v_div_scale_f32 v10, vcc, v139, v7, v139
	v_fma_f32 v11, -v8, v9, 1.0
	v_fmac_f32_e32 v9, v11, v9
	v_mul_f32_e32 v11, v10, v9
	v_fma_f32 v12, -v8, v11, v10
	v_fmac_f32_e32 v11, v12, v9
	v_fma_f32 v8, -v8, v11, v10
	v_div_fmas_f32 v8, v8, v9, v11
	v_div_fixup_f32 v139, v8, v7, v139
	ds_write_b32 v5, v139 offset:47104
	s_waitcnt vmcnt(7)
	v_mul_f32_e32 v7, 0xbfb8aa3b, v140
	v_exp_f32_e32 v7, v7
	s_nop 0
	v_add_f32_e32 v7, 1.0, v7
	v_div_scale_f32 v8, s[8:9], v7, v7, v140
	v_rcp_f32_e32 v9, v8
	v_div_scale_f32 v10, vcc, v140, v7, v140
	v_fma_f32 v11, -v8, v9, 1.0
	v_fmac_f32_e32 v9, v11, v9
	v_mul_f32_e32 v11, v10, v9
	v_fma_f32 v12, -v8, v11, v10
	v_fmac_f32_e32 v11, v12, v9
	v_fma_f32 v8, -v8, v11, v10
	v_div_fmas_f32 v8, v8, v9, v11
	v_div_fixup_f32 v140, v8, v7, v140
	ds_write_b32 v5, v140 offset:49152
	s_waitcnt vmcnt(6)
	v_mul_f32_e32 v7, 0xbfb8aa3b, v141
	v_exp_f32_e32 v7, v7
	s_nop 0
	v_add_f32_e32 v7, 1.0, v7
	v_div_scale_f32 v8, s[8:9], v7, v7, v141
	v_rcp_f32_e32 v9, v8
	v_div_scale_f32 v10, vcc, v141, v7, v141
	v_fma_f32 v11, -v8, v9, 1.0
	v_fmac_f32_e32 v9, v11, v9
	v_mul_f32_e32 v11, v10, v9
	v_fma_f32 v12, -v8, v11, v10
	v_fmac_f32_e32 v11, v12, v9
	v_fma_f32 v8, -v8, v11, v10
	v_div_fmas_f32 v8, v8, v9, v11
	v_div_fixup_f32 v141, v8, v7, v141
	ds_write_b32 v5, v141 offset:51200
	s_waitcnt vmcnt(5)
	v_mul_f32_e32 v7, 0xbfb8aa3b, v142
	v_exp_f32_e32 v7, v7
	s_nop 0
	v_add_f32_e32 v7, 1.0, v7
	v_div_scale_f32 v8, s[8:9], v7, v7, v142
	v_rcp_f32_e32 v9, v8
	v_div_scale_f32 v10, vcc, v142, v7, v142
	v_fma_f32 v11, -v8, v9, 1.0
	v_fmac_f32_e32 v9, v11, v9
	v_mul_f32_e32 v11, v10, v9
	v_fma_f32 v12, -v8, v11, v10
	v_fmac_f32_e32 v11, v12, v9
	v_fma_f32 v8, -v8, v11, v10
	v_div_fmas_f32 v8, v8, v9, v11
	v_div_fixup_f32 v142, v8, v7, v142
	ds_write_b32 v5, v142 offset:53248
	s_waitcnt vmcnt(4)
	v_mul_f32_e32 v7, 0xbfb8aa3b, v143
	v_exp_f32_e32 v7, v7
	s_nop 0
	v_add_f32_e32 v7, 1.0, v7
	v_div_scale_f32 v8, s[8:9], v7, v7, v143
	v_rcp_f32_e32 v9, v8
	v_div_scale_f32 v10, vcc, v143, v7, v143
	v_fma_f32 v11, -v8, v9, 1.0
	v_fmac_f32_e32 v9, v11, v9
	v_mul_f32_e32 v11, v10, v9
	v_fma_f32 v12, -v8, v11, v10
	v_fmac_f32_e32 v11, v12, v9
	v_fma_f32 v8, -v8, v11, v10
	v_div_fmas_f32 v8, v8, v9, v11
	v_div_fixup_f32 v143, v8, v7, v143
	ds_write_b32 v5, v143 offset:55296
	s_waitcnt vmcnt(3)
	v_mul_f32_e32 v7, 0xbfb8aa3b, v144
	v_exp_f32_e32 v7, v7
	s_nop 0
	v_add_f32_e32 v7, 1.0, v7
	v_div_scale_f32 v8, s[8:9], v7, v7, v144
	v_rcp_f32_e32 v9, v8
	v_div_scale_f32 v10, vcc, v144, v7, v144
	v_fma_f32 v11, -v8, v9, 1.0
	v_fmac_f32_e32 v9, v11, v9
	v_mul_f32_e32 v11, v10, v9
	v_fma_f32 v12, -v8, v11, v10
	v_fmac_f32_e32 v11, v12, v9
	v_fma_f32 v8, -v8, v11, v10
	v_div_fmas_f32 v8, v8, v9, v11
	v_div_fixup_f32 v144, v8, v7, v144
	ds_write_b32 v5, v144 offset:57344
	s_waitcnt vmcnt(2)
	v_mul_f32_e32 v7, 0xbfb8aa3b, v145
	v_exp_f32_e32 v7, v7
	s_nop 0
	v_add_f32_e32 v7, 1.0, v7
	v_div_scale_f32 v8, s[8:9], v7, v7, v145
	v_rcp_f32_e32 v9, v8
	v_div_scale_f32 v10, vcc, v145, v7, v145
	v_fma_f32 v11, -v8, v9, 1.0
	v_fmac_f32_e32 v9, v11, v9
	v_mul_f32_e32 v11, v10, v9
	v_fma_f32 v12, -v8, v11, v10
	v_fmac_f32_e32 v11, v12, v9
	v_fma_f32 v8, -v8, v11, v10
	v_div_fmas_f32 v8, v8, v9, v11
	v_div_fixup_f32 v145, v8, v7, v145
	ds_write_b32 v5, v145 offset:59392
	s_waitcnt vmcnt(1)
	v_mul_f32_e32 v7, 0xbfb8aa3b, v146
	v_exp_f32_e32 v7, v7
	s_nop 0
	v_add_f32_e32 v7, 1.0, v7
	v_div_scale_f32 v8, s[8:9], v7, v7, v146
	v_rcp_f32_e32 v9, v8
	v_div_scale_f32 v10, vcc, v146, v7, v146
	v_fma_f32 v11, -v8, v9, 1.0
	v_fmac_f32_e32 v9, v11, v9
	v_mul_f32_e32 v11, v10, v9
	v_fma_f32 v12, -v8, v11, v10
	v_fmac_f32_e32 v11, v12, v9
	v_fma_f32 v8, -v8, v11, v10
	v_div_fmas_f32 v8, v8, v9, v11
	v_div_fixup_f32 v146, v8, v7, v146
	ds_write_b32 v5, v146 offset:61440
	s_waitcnt vmcnt(0)
	v_mul_f32_e32 v7, 0xbfb8aa3b, v147
	v_exp_f32_e32 v7, v7
	s_nop 0
	v_add_f32_e32 v7, 1.0, v7
	v_div_scale_f32 v8, s[8:9], v7, v7, v147
	v_rcp_f32_e32 v9, v8
	v_div_scale_f32 v10, vcc, v147, v7, v147
	v_fma_f32 v11, -v8, v9, 1.0
	v_fmac_f32_e32 v9, v11, v9
	v_mul_f32_e32 v11, v10, v9
	v_fma_f32 v12, -v8, v11, v10
	v_fmac_f32_e32 v11, v12, v9
	v_fma_f32 v8, -v8, v11, v10
	v_div_fmas_f32 v8, v8, v9, v11
	v_div_fixup_f32 v147, v8, v7, v147
	ds_write_b32 v5, v147 offset:63488
	s_lshr_b32 s0, s33, 6
	s_add_u32 s72, s76, 0x100000
	s_addc_u32 s73, s77, 0
	v_and_b32_e32 v67, 63, v1
	v_writelane_b32 v253, s0, 16
	s_cmpk_gt_i32 s2, 0xff
	s_waitcnt lgkmcnt(0)
	s_barrier
	s_cbranch_scc1 .LBB0_17
	v_readlane_b32 s7, v253, 16
	s_lshl_b32 s0, s7, 7
	s_add_i32 s3, 0, 0x10000
	s_mul_i32 s6, s7, 0x480000
	v_lshlrev_b32_e32 v2, 2, v67
	v_cmp_gt_u32_e32 vcc, 36, v67
	s_mul_hi_i32 s0, s0, 0x9000
	s_add_u32 s13, s88, s6
	v_cndmask_b32_e32 v74, 0, v2, vcc
	v_lshl_add_u32 v2, v67, 4, s3
	s_mul_i32 s1, s7, 0x2400
	s_addc_u32 s14, s89, s0
	s_lshl_b32 s0, s7, 9
	s_mov_b32 s12, 0x9000
	s_add_i32 s15, s0, 0
	v_mov_b32_e32 v69, 0
	s_mov_b32 s16, 0x12000
	s_mov_b32 s17, 0x1b000
	v_add_u32_e32 v75, s1, v2
	s_mov_b32 s18, 0xe38f
	s_movk_i32 s19, 0x6ff
	s_mov_b32 s20, s2
	s_mov_b32 s21, s2

.LBB0_11:
	v_lshl_add_u64 v[232:233], v[70:71], 0, 0
	s_mov_b64 s[0:1], 0x9000
	global_load_dwordx4 v[76:79], v[232:233], off
	v_lshl_add_u64 v[232:233], v[232:233], 0, s[0:1]
	global_load_dwordx4 v[144:147], v[232:233], off
	v_lshl_add_u64 v[232:233], v[232:233], 0, s[0:1]
	global_load_dwordx4 v[148:151], v[232:233], off
	v_lshl_add_u64 v[232:233], v[232:233], 0, s[0:1]
	global_load_dwordx4 v[152:155], v[232:233], off
	v_lshl_add_u64 v[232:233], v[232:233], 0, s[0:1]
	global_load_dwordx4 v[184:187], v[232:233], off
	v_lshl_add_u64 v[232:233], v[232:233], 0, s[0:1]
	global_load_dwordx4 v[188:191], v[232:233], off
	v_lshl_add_u64 v[232:233], v[232:233], 0, s[0:1]
	global_load_dwordx4 v[192:195], v[232:233], off
	v_lshl_add_u64 v[232:233], v[232:233], 0, s[0:1]
	global_load_dwordx4 v[196:199], v[232:233], off
	v_lshl_add_u64 v[232:233], v[232:233], 0, s[0:1]
	global_load_dwordx4 v[200:203], v[232:233], off
	v_lshl_add_u64 v[232:233], v[232:233], 0, s[0:1]
	global_load_dwordx4 v[204:207], v[232:233], off
	v_lshl_add_u64 v[232:233], v[232:233], 0, s[0:1]
	global_load_dwordx4 v[208:211], v[232:233], off
	v_lshl_add_u64 v[232:233], v[232:233], 0, s[0:1]
	global_load_dwordx4 v[212:215], v[232:233], off
	v_lshl_add_u64 v[232:233], v[232:233], 0, s[0:1]
	global_load_dwordx4 v[216:219], v[232:233], off
	v_lshl_add_u64 v[232:233], v[232:233], 0, s[0:1]
	global_load_dwordx4 v[220:223], v[232:233], off
	v_lshl_add_u64 v[232:233], v[232:233], 0, s[0:1]
	global_load_dwordx4 v[224:227], v[232:233], off
	v_lshl_add_u64 v[232:233], v[232:233], 0, s[0:1]
	global_load_dwordx4 v[228:231], v[232:233], off
	v_lshl_add_u64 v[232:233], v[232:233], 0, s[0:1]
	s_mov_b32 s8, 0
.Lada_loop:
	v_mov_b32_e32 v68, s10
	ds_read_b128 v[80:83], v68
	ds_read_b128 v[84:87], v68 offset:4096
	ds_read_b128 v[88:91], v68 offset:8192
	ds_read_b128 v[92:95], v68 offset:12288
	ds_read_b128 v[96:99], v68 offset:16384
	ds_read_b128 v[100:103], v68 offset:20480
	ds_read_b128 v[104:107], v68 offset:24576
	ds_read_b128 v[108:111], v68 offset:28672
	ds_read_b128 v[112:115], v68 offset:32768
	ds_read_b128 v[116:119], v68 offset:36864
	ds_read_b128 v[120:123], v68 offset:40960
	ds_read_b128 v[124:127], v68 offset:45056
	ds_read_b128 v[128:131], v68 offset:49152
	ds_read_b128 v[132:135], v68 offset:53248
	ds_read_b128 v[136:139], v68 offset:57344
	ds_read_b128 v[140:143], v68 offset:61440
	s_add_i32 s10, s10, 16
	s_waitcnt lgkmcnt(14)
	v_mov_b32_e32 v68, v83
	v_mov_b32_e32 v72, v87
	s_waitcnt lgkmcnt(13)
	v_mov_b32_e32 v156, v91
	s_waitcnt lgkmcnt(12)
	v_mov_b32_e32 v158, v95
	s_waitcnt lgkmcnt(11)
	v_mov_b32_e32 v160, v99
	s_waitcnt lgkmcnt(10)
	v_mov_b32_e32 v162, v103
	s_waitcnt lgkmcnt(9)
	v_mov_b32_e32 v164, v107
	s_waitcnt lgkmcnt(8)
	v_mov_b32_e32 v166, v111
	s_waitcnt lgkmcnt(7)
	v_mov_b32_e32 v168, v115
	s_waitcnt lgkmcnt(6)
	v_mov_b32_e32 v170, v119
	s_waitcnt lgkmcnt(5)
	v_mov_b32_e32 v172, v123
	s_waitcnt lgkmcnt(4)
	v_mov_b32_e32 v174, v127
	s_waitcnt lgkmcnt(3)
	v_mov_b32_e32 v176, v131
	s_waitcnt lgkmcnt(2)
	v_mov_b32_e32 v178, v135
	s_waitcnt lgkmcnt(1)
	v_mov_b32_e32 v180, v139
	s_waitcnt lgkmcnt(0)
	v_mov_b32_e32 v182, v143
	s_waitcnt vmcnt(15)
	v_pk_fma_f32 v[64:65], v[78:79], v[80:81], v[64:65] op_sel_hi:[1,0,1]
	v_pk_fma_f32 v[62:63], v[76:77], v[80:81], v[62:63] op_sel_hi:[1,0,1]
	v_pk_fma_f32 v[60:61], v[78:79], v[84:85], v[60:61] op_sel_hi:[1,0,1]
	v_pk_fma_f32 v[58:59], v[76:77], v[84:85], v[58:59] op_sel_hi:[1,0,1]
	v_pk_fma_f32 v[56:57], v[78:79], v[88:89], v[56:57] op_sel_hi:[1,0,1]
	v_pk_fma_f32 v[54:55], v[76:77], v[88:89], v[54:55] op_sel_hi:[1,0,1]
	v_pk_fma_f32 v[52:53], v[78:79], v[92:93], v[52:53] op_sel_hi:[1,0,1]
	v_pk_fma_f32 v[50:51], v[76:77], v[92:93], v[50:51] op_sel_hi:[1,0,1]
	v_pk_fma_f32 v[48:49], v[78:79], v[96:97], v[48:49] op_sel_hi:[1,0,1]
	v_pk_fma_f32 v[46:47], v[76:77], v[96:97], v[46:47] op_sel_hi:[1,0,1]
	v_pk_fma_f32 v[44:45], v[78:79], v[100:101], v[44:45] op_sel_hi:[1,0,1]
	v_pk_fma_f32 v[42:43], v[76:77], v[100:101], v[42:43] op_sel_hi:[1,0,1]
	v_pk_fma_f32 v[40:41], v[78:79], v[104:105], v[40:41] op_sel_hi:[1,0,1]
	v_pk_fma_f32 v[38:39], v[76:77], v[104:105], v[38:39] op_sel_hi:[1,0,1]
	v_pk_fma_f32 v[36:37], v[78:79], v[108:109], v[36:37] op_sel_hi:[1,0,1]
	v_pk_fma_f32 v[34:35], v[76:77], v[108:109], v[34:35] op_sel_hi:[1,0,1]
	v_pk_fma_f32 v[32:33], v[78:79], v[112:113], v[32:33] op_sel_hi:[1,0,1]
	v_pk_fma_f32 v[30:31], v[76:77], v[112:113], v[30:31] op_sel_hi:[1,0,1]
	v_pk_fma_f32 v[28:29], v[78:79], v[116:117], v[28:29] op_sel_hi:[1,0,1]
	v_pk_fma_f32 v[26:27], v[76:77], v[116:117], v[26:27] op_sel_hi:[1,0,1]
	v_pk_fma_f32 v[24:25], v[78:79], v[120:121], v[24:25] op_sel_hi:[1,0,1]
	v_pk_fma_f32 v[22:23], v[76:77], v[120:121], v[22:23] op_sel_hi:[1,0,1]
	v_pk_fma_f32 v[20:21], v[78:79], v[124:125], v[20:21] op_sel_hi:[1,0,1]
	v_pk_fma_f32 v[18:19], v[76:77], v[124:125], v[18:19] op_sel_hi:[1,0,1]
	v_pk_fma_f32 v[16:17], v[78:79], v[128:129], v[16:17] op_sel_hi:[1,0,1]
	v_pk_fma_f32 v[14:15], v[76:77], v[128:129], v[14:15] op_sel_hi:[1,0,1]
	v_pk_fma_f32 v[12:13], v[78:79], v[132:133], v[12:13] op_sel_hi:[1,0,1]
	v_pk_fma_f32 v[10:11], v[76:77], v[132:133], v[10:11] op_sel_hi:[1,0,1]
	v_pk_fma_f32 v[8:9], v[78:79], v[136:137], v[8:9] op_sel_hi:[1,0,1]
	v_pk_fma_f32 v[6:7], v[76:77], v[136:137], v[6:7] op_sel_hi:[1,0,1]
	v_pk_fma_f32 v[4:5], v[78:79], v[140:141], v[4:5] op_sel_hi:[1,0,1]
	v_pk_fma_f32 v[2:3], v[76:77], v[140:141], v[2:3] op_sel_hi:[1,0,1]
	global_load_dwordx4 v[76:79], v[232:233], off
	v_lshl_add_u64 v[232:233], v[232:233], 0, s[0:1]
	s_waitcnt vmcnt(15)
	v_pk_fma_f32 v[62:63], v[144:145], v[80:81], v[62:63] op_sel:[0,1,0]
	v_pk_fma_f32 v[64:65], v[146:147], v[80:81], v[64:65] op_sel:[0,1,0]
	v_pk_fma_f32 v[58:59], v[144:145], v[84:85], v[58:59] op_sel:[0,1,0]
	v_pk_fma_f32 v[60:61], v[146:147], v[84:85], v[60:61] op_sel:[0,1,0]
	v_pk_fma_f32 v[54:55], v[144:145], v[88:89], v[54:55] op_sel:[0,1,0]
	v_pk_fma_f32 v[56:57], v[146:147], v[88:89], v[56:57] op_sel:[0,1,0]
	v_pk_fma_f32 v[50:51], v[144:145], v[92:93], v[50:51] op_sel:[0,1,0]
	v_pk_fma_f32 v[52:53], v[146:147], v[92:93], v[52:53] op_sel:[0,1,0]
	v_pk_fma_f32 v[46:47], v[144:145], v[96:97], v[46:47] op_sel:[0,1,0]
	v_pk_fma_f32 v[48:49], v[146:147], v[96:97], v[48:49] op_sel:[0,1,0]
	v_pk_fma_f32 v[42:43], v[144:145], v[100:101], v[42:43] op_sel:[0,1,0]
	v_pk_fma_f32 v[44:45], v[146:147], v[100:101], v[44:45] op_sel:[0,1,0]
	v_pk_fma_f32 v[38:39], v[144:145], v[104:105], v[38:39] op_sel:[0,1,0]
	v_pk_fma_f32 v[40:41], v[146:147], v[104:105], v[40:41] op_sel:[0,1,0]
	v_pk_fma_f32 v[34:35], v[144:145], v[108:109], v[34:35] op_sel:[0,1,0]
	v_pk_fma_f32 v[36:37], v[146:147], v[108:109], v[36:37] op_sel:[0,1,0]
	v_pk_fma_f32 v[30:31], v[144:145], v[112:113], v[30:31] op_sel:[0,1,0]
	v_pk_fma_f32 v[32:33], v[146:147], v[112:113], v[32:33] op_sel:[0,1,0]
	v_pk_fma_f32 v[26:27], v[144:145], v[116:117], v[26:27] op_sel:[0,1,0]
	v_pk_fma_f32 v[28:29], v[146:147], v[116:117], v[28:29] op_sel:[0,1,0]
	v_pk_fma_f32 v[22:23], v[144:145], v[120:121], v[22:23] op_sel:[0,1,0]
	v_pk_fma_f32 v[24:25], v[146:147], v[120:121], v[24:25] op_sel:[0,1,0]
	v_pk_fma_f32 v[18:19], v[144:145], v[124:125], v[18:19] op_sel:[0,1,0]
	v_pk_fma_f32 v[20:21], v[146:147], v[124:125], v[20:21] op_sel:[0,1,0]
	v_pk_fma_f32 v[14:15], v[144:145], v[128:129], v[14:15] op_sel:[0,1,0]
	v_pk_fma_f32 v[16:17], v[146:147], v[128:129], v[16:17] op_sel:[0,1,0]
	v_pk_fma_f32 v[10:11], v[144:145], v[132:133], v[10:11] op_sel:[0,1,0]
	v_pk_fma_f32 v[12:13], v[146:147], v[132:133], v[12:13] op_sel:[0,1,0]
	v_pk_fma_f32 v[6:7], v[144:145], v[136:137], v[6:7] op_sel:[0,1,0]
	v_pk_fma_f32 v[8:9], v[146:147], v[136:137], v[8:9] op_sel:[0,1,0]
	v_pk_fma_f32 v[2:3], v[144:145], v[140:141], v[2:3] op_sel:[0,1,0]
	v_pk_fma_f32 v[4:5], v[146:147], v[140:141], v[4:5] op_sel:[0,1,0]
	global_load_dwordx4 v[144:147], v[232:233], off
	v_lshl_add_u64 v[232:233], v[232:233], 0, s[0:1]
	s_waitcnt vmcnt(15)
	v_pk_fma_f32 v[64:65], v[150:151], v[82:83], v[64:65] op_sel_hi:[1,0,1]
	v_pk_fma_f32 v[62:63], v[148:149], v[82:83], v[62:63] op_sel_hi:[1,0,1]
	v_pk_fma_f32 v[60:61], v[150:151], v[86:87], v[60:61] op_sel_hi:[1,0,1]
	v_pk_fma_f32 v[58:59], v[148:149], v[86:87], v[58:59] op_sel_hi:[1,0,1]
	v_pk_fma_f32 v[56:57], v[150:151], v[90:91], v[56:57] op_sel_hi:[1,0,1]
	v_pk_fma_f32 v[54:55], v[148:149], v[90:91], v[54:55] op_sel_hi:[1,0,1]
	v_pk_fma_f32 v[52:53], v[150:151], v[94:95], v[52:53] op_sel_hi:[1,0,1]
	v_pk_fma_f32 v[50:51], v[148:149], v[94:95], v[50:51] op_sel_hi:[1,0,1]
	v_pk_fma_f32 v[48:49], v[150:151], v[98:99], v[48:49] op_sel_hi:[1,0,1]
	v_pk_fma_f32 v[46:47], v[148:149], v[98:99], v[46:47] op_sel_hi:[1,0,1]
	v_pk_fma_f32 v[44:45], v[150:151], v[102:103], v[44:45] op_sel_hi:[1,0,1]
	v_pk_fma_f32 v[42:43], v[148:149], v[102:103], v[42:43] op_sel_hi:[1,0,1]
	v_pk_fma_f32 v[40:41], v[150:151], v[106:107], v[40:41] op_sel_hi:[1,0,1]
	v_pk_fma_f32 v[38:39], v[148:149], v[106:107], v[38:39] op_sel_hi:[1,0,1]
	v_pk_fma_f32 v[36:37], v[150:151], v[110:111], v[36:37] op_sel_hi:[1,0,1]
	v_pk_fma_f32 v[34:35], v[148:149], v[110:111], v[34:35] op_sel_hi:[1,0,1]
	v_pk_fma_f32 v[32:33], v[150:151], v[114:115], v[32:33] op_sel_hi:[1,0,1]
	v_pk_fma_f32 v[30:31], v[148:149], v[114:115], v[30:31] op_sel_hi:[1,0,1]
	v_pk_fma_f32 v[28:29], v[150:151], v[118:119], v[28:29] op_sel_hi:[1,0,1]
	v_pk_fma_f32 v[26:27], v[148:149], v[118:119], v[26:27] op_sel_hi:[1,0,1]
	v_pk_fma_f32 v[24:25], v[150:151], v[122:123], v[24:25] op_sel_hi:[1,0,1]
	v_pk_fma_f32 v[22:23], v[148:149], v[122:123], v[22:23] op_sel_hi:[1,0,1]
	v_pk_fma_f32 v[20:21], v[150:151], v[126:127], v[20:21] op_sel_hi:[1,0,1]
	v_pk_fma_f32 v[18:19], v[148:149], v[126:127], v[18:19] op_sel_hi:[1,0,1]
	v_pk_fma_f32 v[16:17], v[150:151], v[130:131], v[16:17] op_sel_hi:[1,0,1]
	v_pk_fma_f32 v[14:15], v[148:149], v[130:131], v[14:15] op_sel_hi:[1,0,1]
	v_pk_fma_f32 v[12:13], v[150:151], v[134:135], v[12:13] op_sel_hi:[1,0,1]
	v_pk_fma_f32 v[10:11], v[148:149], v[134:135], v[10:11] op_sel_hi:[1,0,1]
	v_pk_fma_f32 v[8:9], v[150:151], v[138:139], v[8:9] op_sel_hi:[1,0,1]
	v_pk_fma_f32 v[6:7], v[148:149], v[138:139], v[6:7] op_sel_hi:[1,0,1]
	v_pk_fma_f32 v[4:5], v[150:151], v[142:143], v[4:5] op_sel_hi:[1,0,1]
	v_pk_fma_f32 v[2:3], v[148:149], v[142:143], v[2:3] op_sel_hi:[1,0,1]
	global_load_dwordx4 v[148:151], v[232:233], off
	v_lshl_add_u64 v[232:233], v[232:233], 0, s[0:1]
	s_waitcnt vmcnt(15)
	v_pk_fma_f32 v[64:65], v[154:155], v[68:69], v[64:65] op_sel_hi:[1,0,1]
	v_pk_fma_f32 v[62:63], v[152:153], v[68:69], v[62:63] op_sel_hi:[1,0,1]
	v_pk_fma_f32 v[60:61], v[154:155], v[72:73], v[60:61] op_sel_hi:[1,0,1]
	v_pk_fma_f32 v[58:59], v[152:153], v[72:73], v[58:59] op_sel_hi:[1,0,1]
	v_pk_fma_f32 v[56:57], v[154:155], v[156:157], v[56:57] op_sel_hi:[1,0,1]
	v_pk_fma_f32 v[54:55], v[152:153], v[156:157], v[54:55] op_sel_hi:[1,0,1]
	v_pk_fma_f32 v[52:53], v[154:155], v[158:159], v[52:53] op_sel_hi:[1,0,1]
	v_pk_fma_f32 v[50:51], v[152:153], v[158:159], v[50:51] op_sel_hi:[1,0,1]
	v_pk_fma_f32 v[48:49], v[154:155], v[160:161], v[48:49] op_sel_hi:[1,0,1]
	v_pk_fma_f32 v[46:47], v[152:153], v[160:161], v[46:47] op_sel_hi:[1,0,1]
	v_pk_fma_f32 v[44:45], v[154:155], v[162:163], v[44:45] op_sel_hi:[1,0,1]
	v_pk_fma_f32 v[42:43], v[152:153], v[162:163], v[42:43] op_sel_hi:[1,0,1]
	v_pk_fma_f32 v[40:41], v[154:155], v[164:165], v[40:41] op_sel_hi:[1,0,1]
	v_pk_fma_f32 v[38:39], v[152:153], v[164:165], v[38:39] op_sel_hi:[1,0,1]
	v_pk_fma_f32 v[36:37], v[154:155], v[166:167], v[36:37] op_sel_hi:[1,0,1]
	v_pk_fma_f32 v[34:35], v[152:153], v[166:167], v[34:35] op_sel_hi:[1,0,1]
	v_pk_fma_f32 v[32:33], v[154:155], v[168:169], v[32:33] op_sel_hi:[1,0,1]
	v_pk_fma_f32 v[30:31], v[152:153], v[168:169], v[30:31] op_sel_hi:[1,0,1]
	v_pk_fma_f32 v[28:29], v[154:155], v[170:171], v[28:29] op_sel_hi:[1,0,1]
	v_pk_fma_f32 v[26:27], v[152:153], v[170:171], v[26:27] op_sel_hi:[1,0,1]
	v_pk_fma_f32 v[24:25], v[154:155], v[172:173], v[24:25] op_sel_hi:[1,0,1]
	v_pk_fma_f32 v[22:23], v[152:153], v[172:173], v[22:23] op_sel_hi:[1,0,1]
	v_pk_fma_f32 v[20:21], v[154:155], v[174:175], v[20:21] op_sel_hi:[1,0,1]
	v_pk_fma_f32 v[18:19], v[152:153], v[174:175], v[18:19] op_sel_hi:[1,0,1]
	v_pk_fma_f32 v[16:17], v[154:155], v[176:177], v[16:17] op_sel_hi:[1,0,1]
	v_pk_fma_f32 v[14:15], v[152:153], v[176:177], v[14:15] op_sel_hi:[1,0,1]
	v_pk_fma_f32 v[12:13], v[154:155], v[178:179], v[12:13] op_sel_hi:[1,0,1]
	v_pk_fma_f32 v[10:11], v[152:153], v[178:179], v[10:11] op_sel_hi:[1,0,1]
	v_pk_fma_f32 v[8:9], v[154:155], v[180:181], v[8:9] op_sel_hi:[1,0,1]
	v_pk_fma_f32 v[6:7], v[152:153], v[180:181], v[6:7] op_sel_hi:[1,0,1]
	v_pk_fma_f32 v[4:5], v[154:155], v[182:183], v[4:5] op_sel_hi:[1,0,1]
	v_pk_fma_f32 v[2:3], v[152:153], v[182:183], v[2:3] op_sel_hi:[1,0,1]
	global_load_dwordx4 v[152:155], v[232:233], off
	v_lshl_add_u64 v[232:233], v[232:233], 0, s[0:1]
	v_mov_b32_e32 v68, s10
	ds_read_b128 v[80:83], v68
	ds_read_b128 v[84:87], v68 offset:4096
	ds_read_b128 v[88:91], v68 offset:8192
	ds_read_b128 v[92:95], v68 offset:12288
	ds_read_b128 v[96:99], v68 offset:16384
	ds_read_b128 v[100:103], v68 offset:20480
	ds_read_b128 v[104:107], v68 offset:24576
	ds_read_b128 v[108:111], v68 offset:28672
	ds_read_b128 v[112:115], v68 offset:32768
	ds_read_b128 v[116:119], v68 offset:36864
	ds_read_b128 v[120:123], v68 offset:40960
	ds_read_b128 v[124:127], v68 offset:45056
	ds_read_b128 v[128:131], v68 offset:49152
	ds_read_b128 v[132:135], v68 offset:53248
	ds_read_b128 v[136:139], v68 offset:57344
	ds_read_b128 v[140:143], v68 offset:61440
	s_add_i32 s10, s10, 16
	s_waitcnt lgkmcnt(14)
	v_mov_b32_e32 v68, v83
	v_mov_b32_e32 v72, v87
	s_waitcnt lgkmcnt(13)
	v_mov_b32_e32 v156, v91
	s_waitcnt lgkmcnt(12)
	v_mov_b32_e32 v158, v95
	s_waitcnt lgkmcnt(11)
	v_mov_b32_e32 v160, v99
	s_waitcnt lgkmcnt(10)
	v_mov_b32_e32 v162, v103
	s_waitcnt lgkmcnt(9)
	v_mov_b32_e32 v164, v107
	s_waitcnt lgkmcnt(8)
	v_mov_b32_e32 v166, v111
	s_waitcnt lgkmcnt(7)
	v_mov_b32_e32 v168, v115
	s_waitcnt lgkmcnt(6)
	v_mov_b32_e32 v170, v119
	s_waitcnt lgkmcnt(5)
	v_mov_b32_e32 v172, v123
	s_waitcnt lgkmcnt(4)
	v_mov_b32_e32 v174, v127
	s_waitcnt lgkmcnt(3)
	v_mov_b32_e32 v176, v131
	s_waitcnt lgkmcnt(2)
	v_mov_b32_e32 v178, v135
	s_waitcnt lgkmcnt(1)
	v_mov_b32_e32 v180, v139
	s_waitcnt lgkmcnt(0)
	v_mov_b32_e32 v182, v143
	s_waitcnt vmcnt(15)
	v_pk_fma_f32 v[64:65], v[186:187], v[80:81], v[64:65] op_sel_hi:[1,0,1]
	v_pk_fma_f32 v[62:63], v[184:185], v[80:81], v[62:63] op_sel_hi:[1,0,1]
	v_pk_fma_f32 v[60:61], v[186:187], v[84:85], v[60:61] op_sel_hi:[1,0,1]
	v_pk_fma_f32 v[58:59], v[184:185], v[84:85], v[58:59] op_sel_hi:[1,0,1]
	v_pk_fma_f32 v[56:57], v[186:187], v[88:89], v[56:57] op_sel_hi:[1,0,1]
	v_pk_fma_f32 v[54:55], v[184:185], v[88:89], v[54:55] op_sel_hi:[1,0,1]
	v_pk_fma_f32 v[52:53], v[186:187], v[92:93], v[52:53] op_sel_hi:[1,0,1]
	v_pk_fma_f32 v[50:51], v[184:185], v[92:93], v[50:51] op_sel_hi:[1,0,1]
	v_pk_fma_f32 v[48:49], v[186:187], v[96:97], v[48:49] op_sel_hi:[1,0,1]
	v_pk_fma_f32 v[46:47], v[184:185], v[96:97], v[46:47] op_sel_hi:[1,0,1]
	v_pk_fma_f32 v[44:45], v[186:187], v[100:101], v[44:45] op_sel_hi:[1,0,1]
	v_pk_fma_f32 v[42:43], v[184:185], v[100:101], v[42:43] op_sel_hi:[1,0,1]
	v_pk_fma_f32 v[40:41], v[186:187], v[104:105], v[40:41] op_sel_hi:[1,0,1]
	v_pk_fma_f32 v[38:39], v[184:185], v[104:105], v[38:39] op_sel_hi:[1,0,1]
	v_pk_fma_f32 v[36:37], v[186:187], v[108:109], v[36:37] op_sel_hi:[1,0,1]
	v_pk_fma_f32 v[34:35], v[184:185], v[108:109], v[34:35] op_sel_hi:[1,0,1]
	v_pk_fma_f32 v[32:33], v[186:187], v[112:113], v[32:33] op_sel_hi:[1,0,1]
	v_pk_fma_f32 v[30:31], v[184:185], v[112:113], v[30:31] op_sel_hi:[1,0,1]
	v_pk_fma_f32 v[28:29], v[186:187], v[116:117], v[28:29] op_sel_hi:[1,0,1]
	v_pk_fma_f32 v[26:27], v[184:185], v[116:117], v[26:27] op_sel_hi:[1,0,1]
	v_pk_fma_f32 v[24:25], v[186:187], v[120:121], v[24:25] op_sel_hi:[1,0,1]
	v_pk_fma_f32 v[22:23], v[184:185], v[120:121], v[22:23] op_sel_hi:[1,0,1]
	v_pk_fma_f32 v[20:21], v[186:187], v[124:125], v[20:21] op_sel_hi:[1,0,1]
	v_pk_fma_f32 v[18:19], v[184:185], v[124:125], v[18:19] op_sel_hi:[1,0,1]
	v_pk_fma_f32 v[16:17], v[186:187], v[128:129], v[16:17] op_sel_hi:[1,0,1]
	v_pk_fma_f32 v[14:15], v[184:185], v[128:129], v[14:15] op_sel_hi:[1,0,1]
	v_pk_fma_f32 v[12:13], v[186:187], v[132:133], v[12:13] op_sel_hi:[1,0,1]
	v_pk_fma_f32 v[10:11], v[184:185], v[132:133], v[10:11] op_sel_hi:[1,0,1]
	v_pk_fma_f32 v[8:9], v[186:187], v[136:137], v[8:9] op_sel_hi:[1,0,1]
	v_pk_fma_f32 v[6:7], v[184:185], v[136:137], v[6:7] op_sel_hi:[1,0,1]
	v_pk_fma_f32 v[4:5], v[186:187], v[140:141], v[4:5] op_sel_hi:[1,0,1]
	v_pk_fma_f32 v[2:3], v[184:185], v[140:141], v[2:3] op_sel_hi:[1,0,1]
	global_load_dwordx4 v[184:187], v[232:233], off
	v_lshl_add_u64 v[232:233], v[232:233], 0, s[0:1]
	s_waitcnt vmcnt(15)
	v_pk_fma_f32 v[62:63], v[188:189], v[80:81], v[62:63] op_sel:[0,1,0]
	v_pk_fma_f32 v[64:65], v[190:191], v[80:81], v[64:65] op_sel:[0,1,0]
	v_pk_fma_f32 v[58:59], v[188:189], v[84:85], v[58:59] op_sel:[0,1,0]
	v_pk_fma_f32 v[60:61], v[190:191], v[84:85], v[60:61] op_sel:[0,1,0]
	v_pk_fma_f32 v[54:55], v[188:189], v[88:89], v[54:55] op_sel:[0,1,0]
	v_pk_fma_f32 v[56:57], v[190:191], v[88:89], v[56:57] op_sel:[0,1,0]
	v_pk_fma_f32 v[50:51], v[188:189], v[92:93], v[50:51] op_sel:[0,1,0]
	v_pk_fma_f32 v[52:53], v[190:191], v[92:93], v[52:53] op_sel:[0,1,0]
	v_pk_fma_f32 v[46:47], v[188:189], v[96:97], v[46:47] op_sel:[0,1,0]
	v_pk_fma_f32 v[48:49], v[190:191], v[96:97], v[48:49] op_sel:[0,1,0]
	v_pk_fma_f32 v[42:43], v[188:189], v[100:101], v[42:43] op_sel:[0,1,0]
	v_pk_fma_f32 v[44:45], v[190:191], v[100:101], v[44:45] op_sel:[0,1,0]
	v_pk_fma_f32 v[38:39], v[188:189], v[104:105], v[38:39] op_sel:[0,1,0]
	v_pk_fma_f32 v[40:41], v[190:191], v[104:105], v[40:41] op_sel:[0,1,0]
	v_pk_fma_f32 v[34:35], v[188:189], v[108:109], v[34:35] op_sel:[0,1,0]
	v_pk_fma_f32 v[36:37], v[190:191], v[108:109], v[36:37] op_sel:[0,1,0]
	v_pk_fma_f32 v[30:31], v[188:189], v[112:113], v[30:31] op_sel:[0,1,0]
	v_pk_fma_f32 v[32:33], v[190:191], v[112:113], v[32:33] op_sel:[0,1,0]
	v_pk_fma_f32 v[26:27], v[188:189], v[116:117], v[26:27] op_sel:[0,1,0]
	v_pk_fma_f32 v[28:29], v[190:191], v[116:117], v[28:29] op_sel:[0,1,0]
	v_pk_fma_f32 v[22:23], v[188:189], v[120:121], v[22:23] op_sel:[0,1,0]
	v_pk_fma_f32 v[24:25], v[190:191], v[120:121], v[24:25] op_sel:[0,1,0]
	v_pk_fma_f32 v[18:19], v[188:189], v[124:125], v[18:19] op_sel:[0,1,0]
	v_pk_fma_f32 v[20:21], v[190:191], v[124:125], v[20:21] op_sel:[0,1,0]
	v_pk_fma_f32 v[14:15], v[188:189], v[128:129], v[14:15] op_sel:[0,1,0]
	v_pk_fma_f32 v[16:17], v[190:191], v[128:129], v[16:17] op_sel:[0,1,0]
	v_pk_fma_f32 v[10:11], v[188:189], v[132:133], v[10:11] op_sel:[0,1,0]
	v_pk_fma_f32 v[12:13], v[190:191], v[132:133], v[12:13] op_sel:[0,1,0]
	v_pk_fma_f32 v[6:7], v[188:189], v[136:137], v[6:7] op_sel:[0,1,0]
	v_pk_fma_f32 v[8:9], v[190:191], v[136:137], v[8:9] op_sel:[0,1,0]
	v_pk_fma_f32 v[2:3], v[188:189], v[140:141], v[2:3] op_sel:[0,1,0]
	v_pk_fma_f32 v[4:5], v[190:191], v[140:141], v[4:5] op_sel:[0,1,0]
	global_load_dwordx4 v[188:191], v[232:233], off
	v_lshl_add_u64 v[232:233], v[232:233], 0, s[0:1]
	s_waitcnt vmcnt(15)
	v_pk_fma_f32 v[64:65], v[194:195], v[82:83], v[64:65] op_sel_hi:[1,0,1]
	v_pk_fma_f32 v[62:63], v[192:193], v[82:83], v[62:63] op_sel_hi:[1,0,1]
	v_pk_fma_f32 v[60:61], v[194:195], v[86:87], v[60:61] op_sel_hi:[1,0,1]
	v_pk_fma_f32 v[58:59], v[192:193], v[86:87], v[58:59] op_sel_hi:[1,0,1]
	v_pk_fma_f32 v[56:57], v[194:195], v[90:91], v[56:57] op_sel_hi:[1,0,1]
	v_pk_fma_f32 v[54:55], v[192:193], v[90:91], v[54:55] op_sel_hi:[1,0,1]
	v_pk_fma_f32 v[52:53], v[194:195], v[94:95], v[52:53] op_sel_hi:[1,0,1]
	v_pk_fma_f32 v[50:51], v[192:193], v[94:95], v[50:51] op_sel_hi:[1,0,1]
	v_pk_fma_f32 v[48:49], v[194:195], v[98:99], v[48:49] op_sel_hi:[1,0,1]
	v_pk_fma_f32 v[46:47], v[192:193], v[98:99], v[46:47] op_sel_hi:[1,0,1]
	v_pk_fma_f32 v[44:45], v[194:195], v[102:103], v[44:45] op_sel_hi:[1,0,1]
	v_pk_fma_f32 v[42:43], v[192:193], v[102:103], v[42:43] op_sel_hi:[1,0,1]
	v_pk_fma_f32 v[40:41], v[194:195], v[106:107], v[40:41] op_sel_hi:[1,0,1]
	v_pk_fma_f32 v[38:39], v[192:193], v[106:107], v[38:39] op_sel_hi:[1,0,1]
	v_pk_fma_f32 v[36:37], v[194:195], v[110:111], v[36:37] op_sel_hi:[1,0,1]
	v_pk_fma_f32 v[34:35], v[192:193], v[110:111], v[34:35] op_sel_hi:[1,0,1]
	v_pk_fma_f32 v[32:33], v[194:195], v[114:115], v[32:33] op_sel_hi:[1,0,1]
	v_pk_fma_f32 v[30:31], v[192:193], v[114:115], v[30:31] op_sel_hi:[1,0,1]
	v_pk_fma_f32 v[28:29], v[194:195], v[118:119], v[28:29] op_sel_hi:[1,0,1]
	v_pk_fma_f32 v[26:27], v[192:193], v[118:119], v[26:27] op_sel_hi:[1,0,1]
	v_pk_fma_f32 v[24:25], v[194:195], v[122:123], v[24:25] op_sel_hi:[1,0,1]
	v_pk_fma_f32 v[22:23], v[192:193], v[122:123], v[22:23] op_sel_hi:[1,0,1]
	v_pk_fma_f32 v[20:21], v[194:195], v[126:127], v[20:21] op_sel_hi:[1,0,1]
	v_pk_fma_f32 v[18:19], v[192:193], v[126:127], v[18:19] op_sel_hi:[1,0,1]
	v_pk_fma_f32 v[16:17], v[194:195], v[130:131], v[16:17] op_sel_hi:[1,0,1]
	v_pk_fma_f32 v[14:15], v[192:193], v[130:131], v[14:15] op_sel_hi:[1,0,1]
	v_pk_fma_f32 v[12:13], v[194:195], v[134:135], v[12:13] op_sel_hi:[1,0,1]
	v_pk_fma_f32 v[10:11], v[192:193], v[134:135], v[10:11] op_sel_hi:[1,0,1]
	v_pk_fma_f32 v[8:9], v[194:195], v[138:139], v[8:9] op_sel_hi:[1,0,1]
	v_pk_fma_f32 v[6:7], v[192:193], v[138:139], v[6:7] op_sel_hi:[1,0,1]
	v_pk_fma_f32 v[4:5], v[194:195], v[142:143], v[4:5] op_sel_hi:[1,0,1]
	v_pk_fma_f32 v[2:3], v[192:193], v[142:143], v[2:3] op_sel_hi:[1,0,1]
	global_load_dwordx4 v[192:195], v[232:233], off
	v_lshl_add_u64 v[232:233], v[232:233], 0, s[0:1]
	s_waitcnt vmcnt(15)
	v_pk_fma_f32 v[64:65], v[198:199], v[68:69], v[64:65] op_sel_hi:[1,0,1]
	v_pk_fma_f32 v[62:63], v[196:197], v[68:69], v[62:63] op_sel_hi:[1,0,1]
	v_pk_fma_f32 v[60:61], v[198:199], v[72:73], v[60:61] op_sel_hi:[1,0,1]
	v_pk_fma_f32 v[58:59], v[196:197], v[72:73], v[58:59] op_sel_hi:[1,0,1]
	v_pk_fma_f32 v[56:57], v[198:199], v[156:157], v[56:57] op_sel_hi:[1,0,1]
	v_pk_fma_f32 v[54:55], v[196:197], v[156:157], v[54:55] op_sel_hi:[1,0,1]
	v_pk_fma_f32 v[52:53], v[198:199], v[158:159], v[52:53] op_sel_hi:[1,0,1]
	v_pk_fma_f32 v[50:51], v[196:197], v[158:159], v[50:51] op_sel_hi:[1,0,1]
	v_pk_fma_f32 v[48:49], v[198:199], v[160:161], v[48:49] op_sel_hi:[1,0,1]
	v_pk_fma_f32 v[46:47], v[196:197], v[160:161], v[46:47] op_sel_hi:[1,0,1]
	v_pk_fma_f32 v[44:45], v[198:199], v[162:163], v[44:45] op_sel_hi:[1,0,1]
	v_pk_fma_f32 v[42:43], v[196:197], v[162:163], v[42:43] op_sel_hi:[1,0,1]
	v_pk_fma_f32 v[40:41], v[198:199], v[164:165], v[40:41] op_sel_hi:[1,0,1]
	v_pk_fma_f32 v[38:39], v[196:197], v[164:165], v[38:39] op_sel_hi:[1,0,1]
	v_pk_fma_f32 v[36:37], v[198:199], v[166:167], v[36:37] op_sel_hi:[1,0,1]
	v_pk_fma_f32 v[34:35], v[196:197], v[166:167], v[34:35] op_sel_hi:[1,0,1]
	v_pk_fma_f32 v[32:33], v[198:199], v[168:169], v[32:33] op_sel_hi:[1,0,1]
	v_pk_fma_f32 v[30:31], v[196:197], v[168:169], v[30:31] op_sel_hi:[1,0,1]
	v_pk_fma_f32 v[28:29], v[198:199], v[170:171], v[28:29] op_sel_hi:[1,0,1]
	v_pk_fma_f32 v[26:27], v[196:197], v[170:171], v[26:27] op_sel_hi:[1,0,1]
	v_pk_fma_f32 v[24:25], v[198:199], v[172:173], v[24:25] op_sel_hi:[1,0,1]
	v_pk_fma_f32 v[22:23], v[196:197], v[172:173], v[22:23] op_sel_hi:[1,0,1]
	v_pk_fma_f32 v[20:21], v[198:199], v[174:175], v[20:21] op_sel_hi:[1,0,1]
	v_pk_fma_f32 v[18:19], v[196:197], v[174:175], v[18:19] op_sel_hi:[1,0,1]
	v_pk_fma_f32 v[16:17], v[198:199], v[176:177], v[16:17] op_sel_hi:[1,0,1]
	v_pk_fma_f32 v[14:15], v[196:197], v[176:177], v[14:15] op_sel_hi:[1,0,1]
	v_pk_fma_f32 v[12:13], v[198:199], v[178:179], v[12:13] op_sel_hi:[1,0,1]
	v_pk_fma_f32 v[10:11], v[196:197], v[178:179], v[10:11] op_sel_hi:[1,0,1]
	v_pk_fma_f32 v[8:9], v[198:199], v[180:181], v[8:9] op_sel_hi:[1,0,1]
	v_pk_fma_f32 v[6:7], v[196:197], v[180:181], v[6:7] op_sel_hi:[1,0,1]
	v_pk_fma_f32 v[4:5], v[198:199], v[182:183], v[4:5] op_sel_hi:[1,0,1]
	v_pk_fma_f32 v[2:3], v[196:197], v[182:183], v[2:3] op_sel_hi:[1,0,1]
	global_load_dwordx4 v[196:199], v[232:233], off
	v_lshl_add_u64 v[232:233], v[232:233], 0, s[0:1]
	v_mov_b32_e32 v68, s10
	ds_read_b128 v[80:83], v68
	ds_read_b128 v[84:87], v68 offset:4096
	ds_read_b128 v[88:91], v68 offset:8192
	ds_read_b128 v[92:95], v68 offset:12288
	ds_read_b128 v[96:99], v68 offset:16384
	ds_read_b128 v[100:103], v68 offset:20480
	ds_read_b128 v[104:107], v68 offset:24576
	ds_read_b128 v[108:111], v68 offset:28672
	ds_read_b128 v[112:115], v68 offset:32768
	ds_read_b128 v[116:119], v68 offset:36864
	ds_read_b128 v[120:123], v68 offset:40960
	ds_read_b128 v[124:127], v68 offset:45056
	ds_read_b128 v[128:131], v68 offset:49152
	ds_read_b128 v[132:135], v68 offset:53248
	ds_read_b128 v[136:139], v68 offset:57344
	ds_read_b128 v[140:143], v68 offset:61440
	s_add_i32 s10, s10, 16
	s_waitcnt lgkmcnt(14)
	v_mov_b32_e32 v68, v83
	v_mov_b32_e32 v72, v87
	s_waitcnt lgkmcnt(13)
	v_mov_b32_e32 v156, v91
	s_waitcnt lgkmcnt(12)
	v_mov_b32_e32 v158, v95
	s_waitcnt lgkmcnt(11)
	v_mov_b32_e32 v160, v99
	s_waitcnt lgkmcnt(10)
	v_mov_b32_e32 v162, v103
	s_waitcnt lgkmcnt(9)
	v_mov_b32_e32 v164, v107
	s_waitcnt lgkmcnt(8)
	v_mov_b32_e32 v166, v111
	s_waitcnt lgkmcnt(7)
	v_mov_b32_e32 v168, v115
	s_waitcnt lgkmcnt(6)
	v_mov_b32_e32 v170, v119
	s_waitcnt lgkmcnt(5)
	v_mov_b32_e32 v172, v123
	s_waitcnt lgkmcnt(4)
	v_mov_b32_e32 v174, v127
	s_waitcnt lgkmcnt(3)
	v_mov_b32_e32 v176, v131
	s_waitcnt lgkmcnt(2)
	v_mov_b32_e32 v178, v135
	s_waitcnt lgkmcnt(1)
	v_mov_b32_e32 v180, v139
	s_waitcnt lgkmcnt(0)
	v_mov_b32_e32 v182, v143
	s_waitcnt vmcnt(15)
	v_pk_fma_f32 v[64:65], v[202:203], v[80:81], v[64:65] op_sel_hi:[1,0,1]
	v_pk_fma_f32 v[62:63], v[200:201], v[80:81], v[62:63] op_sel_hi:[1,0,1]
	v_pk_fma_f32 v[60:61], v[202:203], v[84:85], v[60:61] op_sel_hi:[1,0,1]
	v_pk_fma_f32 v[58:59], v[200:201], v[84:85], v[58:59] op_sel_hi:[1,0,1]
	v_pk_fma_f32 v[56:57], v[202:203], v[88:89], v[56:57] op_sel_hi:[1,0,1]
	v_pk_fma_f32 v[54:55], v[200:201], v[88:89], v[54:55] op_sel_hi:[1,0,1]
	v_pk_fma_f32 v[52:53], v[202:203], v[92:93], v[52:53] op_sel_hi:[1,0,1]
	v_pk_fma_f32 v[50:51], v[200:201], v[92:93], v[50:51] op_sel_hi:[1,0,1]
	v_pk_fma_f32 v[48:49], v[202:203], v[96:97], v[48:49] op_sel_hi:[1,0,1]
	v_pk_fma_f32 v[46:47], v[200:201], v[96:97], v[46:47] op_sel_hi:[1,0,1]
	v_pk_fma_f32 v[44:45], v[202:203], v[100:101], v[44:45] op_sel_hi:[1,0,1]
	v_pk_fma_f32 v[42:43], v[200:201], v[100:101], v[42:43] op_sel_hi:[1,0,1]
	v_pk_fma_f32 v[40:41], v[202:203], v[104:105], v[40:41] op_sel_hi:[1,0,1]
	v_pk_fma_f32 v[38:39], v[200:201], v[104:105], v[38:39] op_sel_hi:[1,0,1]
	v_pk_fma_f32 v[36:37], v[202:203], v[108:109], v[36:37] op_sel_hi:[1,0,1]
	v_pk_fma_f32 v[34:35], v[200:201], v[108:109], v[34:35] op_sel_hi:[1,0,1]
	v_pk_fma_f32 v[32:33], v[202:203], v[112:113], v[32:33] op_sel_hi:[1,0,1]
	v_pk_fma_f32 v[30:31], v[200:201], v[112:113], v[30:31] op_sel_hi:[1,0,1]
	v_pk_fma_f32 v[28:29], v[202:203], v[116:117], v[28:29] op_sel_hi:[1,0,1]
	v_pk_fma_f32 v[26:27], v[200:201], v[116:117], v[26:27] op_sel_hi:[1,0,1]
	v_pk_fma_f32 v[24:25], v[202:203], v[120:121], v[24:25] op_sel_hi:[1,0,1]
	v_pk_fma_f32 v[22:23], v[200:201], v[120:121], v[22:23] op_sel_hi:[1,0,1]
	v_pk_fma_f32 v[20:21], v[202:203], v[124:125], v[20:21] op_sel_hi:[1,0,1]
	v_pk_fma_f32 v[18:19], v[200:201], v[124:125], v[18:19] op_sel_hi:[1,0,1]
	v_pk_fma_f32 v[16:17], v[202:203], v[128:129], v[16:17] op_sel_hi:[1,0,1]
	v_pk_fma_f32 v[14:15], v[200:201], v[128:129], v[14:15] op_sel_hi:[1,0,1]
	v_pk_fma_f32 v[12:13], v[202:203], v[132:133], v[12:13] op_sel_hi:[1,0,1]
	v_pk_fma_f32 v[10:11], v[200:201], v[132:133], v[10:11] op_sel_hi:[1,0,1]
	v_pk_fma_f32 v[8:9], v[202:203], v[136:137], v[8:9] op_sel_hi:[1,0,1]
	v_pk_fma_f32 v[6:7], v[200:201], v[136:137], v[6:7] op_sel_hi:[1,0,1]
	v_pk_fma_f32 v[4:5], v[202:203], v[140:141], v[4:5] op_sel_hi:[1,0,1]
	v_pk_fma_f32 v[2:3], v[200:201], v[140:141], v[2:3] op_sel_hi:[1,0,1]
	global_load_dwordx4 v[200:203], v[232:233], off
	v_lshl_add_u64 v[232:233], v[232:233], 0, s[0:1]
	s_waitcnt vmcnt(15)
	v_pk_fma_f32 v[62:63], v[204:205], v[80:81], v[62:63] op_sel:[0,1,0]
	v_pk_fma_f32 v[64:65], v[206:207], v[80:81], v[64:65] op_sel:[0,1,0]
	v_pk_fma_f32 v[58:59], v[204:205], v[84:85], v[58:59] op_sel:[0,1,0]
	v_pk_fma_f32 v[60:61], v[206:207], v[84:85], v[60:61] op_sel:[0,1,0]
	v_pk_fma_f32 v[54:55], v[204:205], v[88:89], v[54:55] op_sel:[0,1,0]
	v_pk_fma_f32 v[56:57], v[206:207], v[88:89], v[56:57] op_sel:[0,1,0]
	v_pk_fma_f32 v[50:51], v[204:205], v[92:93], v[50:51] op_sel:[0,1,0]
	v_pk_fma_f32 v[52:53], v[206:207], v[92:93], v[52:53] op_sel:[0,1,0]
	v_pk_fma_f32 v[46:47], v[204:205], v[96:97], v[46:47] op_sel:[0,1,0]
	v_pk_fma_f32 v[48:49], v[206:207], v[96:97], v[48:49] op_sel:[0,1,0]
	v_pk_fma_f32 v[42:43], v[204:205], v[100:101], v[42:43] op_sel:[0,1,0]
	v_pk_fma_f32 v[44:45], v[206:207], v[100:101], v[44:45] op_sel:[0,1,0]
	v_pk_fma_f32 v[38:39], v[204:205], v[104:105], v[38:39] op_sel:[0,1,0]
	v_pk_fma_f32 v[40:41], v[206:207], v[104:105], v[40:41] op_sel:[0,1,0]
	v_pk_fma_f32 v[34:35], v[204:205], v[108:109], v[34:35] op_sel:[0,1,0]
	v_pk_fma_f32 v[36:37], v[206:207], v[108:109], v[36:37] op_sel:[0,1,0]
	v_pk_fma_f32 v[30:31], v[204:205], v[112:113], v[30:31] op_sel:[0,1,0]
	v_pk_fma_f32 v[32:33], v[206:207], v[112:113], v[32:33] op_sel:[0,1,0]
	v_pk_fma_f32 v[26:27], v[204:205], v[116:117], v[26:27] op_sel:[0,1,0]
	v_pk_fma_f32 v[28:29], v[206:207], v[116:117], v[28:29] op_sel:[0,1,0]
	v_pk_fma_f32 v[22:23], v[204:205], v[120:121], v[22:23] op_sel:[0,1,0]
	v_pk_fma_f32 v[24:25], v[206:207], v[120:121], v[24:25] op_sel:[0,1,0]
	v_pk_fma_f32 v[18:19], v[204:205], v[124:125], v[18:19] op_sel:[0,1,0]
	v_pk_fma_f32 v[20:21], v[206:207], v[124:125], v[20:21] op_sel:[0,1,0]
	v_pk_fma_f32 v[14:15], v[204:205], v[128:129], v[14:15] op_sel:[0,1,0]
	v_pk_fma_f32 v[16:17], v[206:207], v[128:129], v[16:17] op_sel:[0,1,0]
	v_pk_fma_f32 v[10:11], v[204:205], v[132:133], v[10:11] op_sel:[0,1,0]
	v_pk_fma_f32 v[12:13], v[206:207], v[132:133], v[12:13] op_sel:[0,1,0]
	v_pk_fma_f32 v[6:7], v[204:205], v[136:137], v[6:7] op_sel:[0,1,0]
	v_pk_fma_f32 v[8:9], v[206:207], v[136:137], v[8:9] op_sel:[0,1,0]
	v_pk_fma_f32 v[2:3], v[204:205], v[140:141], v[2:3] op_sel:[0,1,0]
	v_pk_fma_f32 v[4:5], v[206:207], v[140:141], v[4:5] op_sel:[0,1,0]
	global_load_dwordx4 v[204:207], v[232:233], off
	v_lshl_add_u64 v[232:233], v[232:233], 0, s[0:1]
	s_waitcnt vmcnt(15)
	v_pk_fma_f32 v[64:65], v[210:211], v[82:83], v[64:65] op_sel_hi:[1,0,1]
	v_pk_fma_f32 v[62:63], v[208:209], v[82:83], v[62:63] op_sel_hi:[1,0,1]
	v_pk_fma_f32 v[60:61], v[210:211], v[86:87], v[60:61] op_sel_hi:[1,0,1]
	v_pk_fma_f32 v[58:59], v[208:209], v[86:87], v[58:59] op_sel_hi:[1,0,1]
	v_pk_fma_f32 v[56:57], v[210:211], v[90:91], v[56:57] op_sel_hi:[1,0,1]
	v_pk_fma_f32 v[54:55], v[208:209], v[90:91], v[54:55] op_sel_hi:[1,0,1]
	v_pk_fma_f32 v[52:53], v[210:211], v[94:95], v[52:53] op_sel_hi:[1,0,1]
	v_pk_fma_f32 v[50:51], v[208:209], v[94:95], v[50:51] op_sel_hi:[1,0,1]
	v_pk_fma_f32 v[48:49], v[210:211], v[98:99], v[48:49] op_sel_hi:[1,0,1]
	v_pk_fma_f32 v[46:47], v[208:209], v[98:99], v[46:47] op_sel_hi:[1,0,1]
	v_pk_fma_f32 v[44:45], v[210:211], v[102:103], v[44:45] op_sel_hi:[1,0,1]
	v_pk_fma_f32 v[42:43], v[208:209], v[102:103], v[42:43] op_sel_hi:[1,0,1]
	v_pk_fma_f32 v[40:41], v[210:211], v[106:107], v[40:41] op_sel_hi:[1,0,1]
	v_pk_fma_f32 v[38:39], v[208:209], v[106:107], v[38:39] op_sel_hi:[1,0,1]
	v_pk_fma_f32 v[36:37], v[210:211], v[110:111], v[36:37] op_sel_hi:[1,0,1]
	v_pk_fma_f32 v[34:35], v[208:209], v[110:111], v[34:35] op_sel_hi:[1,0,1]
	v_pk_fma_f32 v[32:33], v[210:211], v[114:115], v[32:33] op_sel_hi:[1,0,1]
	v_pk_fma_f32 v[30:31], v[208:209], v[114:115], v[30:31] op_sel_hi:[1,0,1]
	v_pk_fma_f32 v[28:29], v[210:211], v[118:119], v[28:29] op_sel_hi:[1,0,1]
	v_pk_fma_f32 v[26:27], v[208:209], v[118:119], v[26:27] op_sel_hi:[1,0,1]
	v_pk_fma_f32 v[24:25], v[210:211], v[122:123], v[24:25] op_sel_hi:[1,0,1]
	v_pk_fma_f32 v[22:23], v[208:209], v[122:123], v[22:23] op_sel_hi:[1,0,1]
	v_pk_fma_f32 v[20:21], v[210:211], v[126:127], v[20:21] op_sel_hi:[1,0,1]
	v_pk_fma_f32 v[18:19], v[208:209], v[126:127], v[18:19] op_sel_hi:[1,0,1]
	v_pk_fma_f32 v[16:17], v[210:211], v[130:131], v[16:17] op_sel_hi:[1,0,1]
	v_pk_fma_f32 v[14:15], v[208:209], v[130:131], v[14:15] op_sel_hi:[1,0,1]
	v_pk_fma_f32 v[12:13], v[210:211], v[134:135], v[12:13] op_sel_hi:[1,0,1]
	v_pk_fma_f32 v[10:11], v[208:209], v[134:135], v[10:11] op_sel_hi:[1,0,1]
	v_pk_fma_f32 v[8:9], v[210:211], v[138:139], v[8:9] op_sel_hi:[1,0,1]
	v_pk_fma_f32 v[6:7], v[208:209], v[138:139], v[6:7] op_sel_hi:[1,0,1]
	v_pk_fma_f32 v[4:5], v[210:211], v[142:143], v[4:5] op_sel_hi:[1,0,1]
	v_pk_fma_f32 v[2:3], v[208:209], v[142:143], v[2:3] op_sel_hi:[1,0,1]
	global_load_dwordx4 v[208:211], v[232:233], off
	v_lshl_add_u64 v[232:233], v[232:233], 0, s[0:1]
	s_waitcnt vmcnt(15)
	v_pk_fma_f32 v[64:65], v[214:215], v[68:69], v[64:65] op_sel_hi:[1,0,1]
	v_pk_fma_f32 v[62:63], v[212:213], v[68:69], v[62:63] op_sel_hi:[1,0,1]
	v_pk_fma_f32 v[60:61], v[214:215], v[72:73], v[60:61] op_sel_hi:[1,0,1]
	v_pk_fma_f32 v[58:59], v[212:213], v[72:73], v[58:59] op_sel_hi:[1,0,1]
	v_pk_fma_f32 v[56:57], v[214:215], v[156:157], v[56:57] op_sel_hi:[1,0,1]
	v_pk_fma_f32 v[54:55], v[212:213], v[156:157], v[54:55] op_sel_hi:[1,0,1]
	v_pk_fma_f32 v[52:53], v[214:215], v[158:159], v[52:53] op_sel_hi:[1,0,1]
	v_pk_fma_f32 v[50:51], v[212:213], v[158:159], v[50:51] op_sel_hi:[1,0,1]
	v_pk_fma_f32 v[48:49], v[214:215], v[160:161], v[48:49] op_sel_hi:[1,0,1]
	v_pk_fma_f32 v[46:47], v[212:213], v[160:161], v[46:47] op_sel_hi:[1,0,1]
	v_pk_fma_f32 v[44:45], v[214:215], v[162:163], v[44:45] op_sel_hi:[1,0,1]
	v_pk_fma_f32 v[42:43], v[212:213], v[162:163], v[42:43] op_sel_hi:[1,0,1]
	v_pk_fma_f32 v[40:41], v[214:215], v[164:165], v[40:41] op_sel_hi:[1,0,1]
	v_pk_fma_f32 v[38:39], v[212:213], v[164:165], v[38:39] op_sel_hi:[1,0,1]
	v_pk_fma_f32 v[36:37], v[214:215], v[166:167], v[36:37] op_sel_hi:[1,0,1]
	v_pk_fma_f32 v[34:35], v[212:213], v[166:167], v[34:35] op_sel_hi:[1,0,1]
	v_pk_fma_f32 v[32:33], v[214:215], v[168:169], v[32:33] op_sel_hi:[1,0,1]
	v_pk_fma_f32 v[30:31], v[212:213], v[168:169], v[30:31] op_sel_hi:[1,0,1]
	v_pk_fma_f32 v[28:29], v[214:215], v[170:171], v[28:29] op_sel_hi:[1,0,1]
	v_pk_fma_f32 v[26:27], v[212:213], v[170:171], v[26:27] op_sel_hi:[1,0,1]
	v_pk_fma_f32 v[24:25], v[214:215], v[172:173], v[24:25] op_sel_hi:[1,0,1]
	v_pk_fma_f32 v[22:23], v[212:213], v[172:173], v[22:23] op_sel_hi:[1,0,1]
	v_pk_fma_f32 v[20:21], v[214:215], v[174:175], v[20:21] op_sel_hi:[1,0,1]
	v_pk_fma_f32 v[18:19], v[212:213], v[174:175], v[18:19] op_sel_hi:[1,0,1]
	v_pk_fma_f32 v[16:17], v[214:215], v[176:177], v[16:17] op_sel_hi:[1,0,1]
	v_pk_fma_f32 v[14:15], v[212:213], v[176:177], v[14:15] op_sel_hi:[1,0,1]
	v_pk_fma_f32 v[12:13], v[214:215], v[178:179], v[12:13] op_sel_hi:[1,0,1]
	v_pk_fma_f32 v[10:11], v[212:213], v[178:179], v[10:11] op_sel_hi:[1,0,1]
	v_pk_fma_f32 v[8:9], v[214:215], v[180:181], v[8:9] op_sel_hi:[1,0,1]
	v_pk_fma_f32 v[6:7], v[212:213], v[180:181], v[6:7] op_sel_hi:[1,0,1]
	v_pk_fma_f32 v[4:5], v[214:215], v[182:183], v[4:5] op_sel_hi:[1,0,1]
	v_pk_fma_f32 v[2:3], v[212:213], v[182:183], v[2:3] op_sel_hi:[1,0,1]
	global_load_dwordx4 v[212:215], v[232:233], off
	v_lshl_add_u64 v[232:233], v[232:233], 0, s[0:1]
	v_mov_b32_e32 v68, s10
	ds_read_b128 v[80:83], v68
	ds_read_b128 v[84:87], v68 offset:4096
	ds_read_b128 v[88:91], v68 offset:8192
	ds_read_b128 v[92:95], v68 offset:12288
	ds_read_b128 v[96:99], v68 offset:16384
	ds_read_b128 v[100:103], v68 offset:20480
	ds_read_b128 v[104:107], v68 offset:24576
	ds_read_b128 v[108:111], v68 offset:28672
	ds_read_b128 v[112:115], v68 offset:32768
	ds_read_b128 v[116:119], v68 offset:36864
	ds_read_b128 v[120:123], v68 offset:40960
	ds_read_b128 v[124:127], v68 offset:45056
	ds_read_b128 v[128:131], v68 offset:49152
	ds_read_b128 v[132:135], v68 offset:53248
	ds_read_b128 v[136:139], v68 offset:57344
	ds_read_b128 v[140:143], v68 offset:61440
	s_add_i32 s10, s10, 16
	s_waitcnt lgkmcnt(14)
	v_mov_b32_e32 v68, v83
	v_mov_b32_e32 v72, v87
	s_waitcnt lgkmcnt(13)
	v_mov_b32_e32 v156, v91
	s_waitcnt lgkmcnt(12)
	v_mov_b32_e32 v158, v95
	s_waitcnt lgkmcnt(11)
	v_mov_b32_e32 v160, v99
	s_waitcnt lgkmcnt(10)
	v_mov_b32_e32 v162, v103
	s_waitcnt lgkmcnt(9)
	v_mov_b32_e32 v164, v107
	s_waitcnt lgkmcnt(8)
	v_mov_b32_e32 v166, v111
	s_waitcnt lgkmcnt(7)
	v_mov_b32_e32 v168, v115
	s_waitcnt lgkmcnt(6)
	v_mov_b32_e32 v170, v119
	s_waitcnt lgkmcnt(5)
	v_mov_b32_e32 v172, v123
	s_waitcnt lgkmcnt(4)
	v_mov_b32_e32 v174, v127
	s_waitcnt lgkmcnt(3)
	v_mov_b32_e32 v176, v131
	s_waitcnt lgkmcnt(2)
	v_mov_b32_e32 v178, v135
	s_waitcnt lgkmcnt(1)
	v_mov_b32_e32 v180, v139
	s_waitcnt lgkmcnt(0)
	v_mov_b32_e32 v182, v143
	s_waitcnt vmcnt(15)
	v_pk_fma_f32 v[64:65], v[218:219], v[80:81], v[64:65] op_sel_hi:[1,0,1]
	v_pk_fma_f32 v[62:63], v[216:217], v[80:81], v[62:63] op_sel_hi:[1,0,1]
	v_pk_fma_f32 v[60:61], v[218:219], v[84:85], v[60:61] op_sel_hi:[1,0,1]
	v_pk_fma_f32 v[58:59], v[216:217], v[84:85], v[58:59] op_sel_hi:[1,0,1]
	v_pk_fma_f32 v[56:57], v[218:219], v[88:89], v[56:57] op_sel_hi:[1,0,1]
	v_pk_fma_f32 v[54:55], v[216:217], v[88:89], v[54:55] op_sel_hi:[1,0,1]
	v_pk_fma_f32 v[52:53], v[218:219], v[92:93], v[52:53] op_sel_hi:[1,0,1]
	v_pk_fma_f32 v[50:51], v[216:217], v[92:93], v[50:51] op_sel_hi:[1,0,1]
	v_pk_fma_f32 v[48:49], v[218:219], v[96:97], v[48:49] op_sel_hi:[1,0,1]
	v_pk_fma_f32 v[46:47], v[216:217], v[96:97], v[46:47] op_sel_hi:[1,0,1]
	v_pk_fma_f32 v[44:45], v[218:219], v[100:101], v[44:45] op_sel_hi:[1,0,1]
	v_pk_fma_f32 v[42:43], v[216:217], v[100:101], v[42:43] op_sel_hi:[1,0,1]
	v_pk_fma_f32 v[40:41], v[218:219], v[104:105], v[40:41] op_sel_hi:[1,0,1]
	v_pk_fma_f32 v[38:39], v[216:217], v[104:105], v[38:39] op_sel_hi:[1,0,1]
	v_pk_fma_f32 v[36:37], v[218:219], v[108:109], v[36:37] op_sel_hi:[1,0,1]
	v_pk_fma_f32 v[34:35], v[216:217], v[108:109], v[34:35] op_sel_hi:[1,0,1]
	v_pk_fma_f32 v[32:33], v[218:219], v[112:113], v[32:33] op_sel_hi:[1,0,1]
	v_pk_fma_f32 v[30:31], v[216:217], v[112:113], v[30:31] op_sel_hi:[1,0,1]
	v_pk_fma_f32 v[28:29], v[218:219], v[116:117], v[28:29] op_sel_hi:[1,0,1]
	v_pk_fma_f32 v[26:27], v[216:217], v[116:117], v[26:27] op_sel_hi:[1,0,1]
	v_pk_fma_f32 v[24:25], v[218:219], v[120:121], v[24:25] op_sel_hi:[1,0,1]
	v_pk_fma_f32 v[22:23], v[216:217], v[120:121], v[22:23] op_sel_hi:[1,0,1]
	v_pk_fma_f32 v[20:21], v[218:219], v[124:125], v[20:21] op_sel_hi:[1,0,1]
	v_pk_fma_f32 v[18:19], v[216:217], v[124:125], v[18:19] op_sel_hi:[1,0,1]
	v_pk_fma_f32 v[16:17], v[218:219], v[128:129], v[16:17] op_sel_hi:[1,0,1]
	v_pk_fma_f32 v[14:15], v[216:217], v[128:129], v[14:15] op_sel_hi:[1,0,1]
	v_pk_fma_f32 v[12:13], v[218:219], v[132:133], v[12:13] op_sel_hi:[1,0,1]
	v_pk_fma_f32 v[10:11], v[216:217], v[132:133], v[10:11] op_sel_hi:[1,0,1]
	v_pk_fma_f32 v[8:9], v[218:219], v[136:137], v[8:9] op_sel_hi:[1,0,1]
	v_pk_fma_f32 v[6:7], v[216:217], v[136:137], v[6:7] op_sel_hi:[1,0,1]
	v_pk_fma_f32 v[4:5], v[218:219], v[140:141], v[4:5] op_sel_hi:[1,0,1]
	v_pk_fma_f32 v[2:3], v[216:217], v[140:141], v[2:3] op_sel_hi:[1,0,1]
	global_load_dwordx4 v[216:219], v[232:233], off
	v_lshl_add_u64 v[232:233], v[232:233], 0, s[0:1]
	s_waitcnt vmcnt(15)
	v_pk_fma_f32 v[62:63], v[220:221], v[80:81], v[62:63] op_sel:[0,1,0]
	v_pk_fma_f32 v[64:65], v[222:223], v[80:81], v[64:65] op_sel:[0,1,0]
	v_pk_fma_f32 v[58:59], v[220:221], v[84:85], v[58:59] op_sel:[0,1,0]
	v_pk_fma_f32 v[60:61], v[222:223], v[84:85], v[60:61] op_sel:[0,1,0]
	v_pk_fma_f32 v[54:55], v[220:221], v[88:89], v[54:55] op_sel:[0,1,0]
	v_pk_fma_f32 v[56:57], v[222:223], v[88:89], v[56:57] op_sel:[0,1,0]
	v_pk_fma_f32 v[50:51], v[220:221], v[92:93], v[50:51] op_sel:[0,1,0]
	v_pk_fma_f32 v[52:53], v[222:223], v[92:93], v[52:53] op_sel:[0,1,0]
	v_pk_fma_f32 v[46:47], v[220:221], v[96:97], v[46:47] op_sel:[0,1,0]
	v_pk_fma_f32 v[48:49], v[222:223], v[96:97], v[48:49] op_sel:[0,1,0]
	v_pk_fma_f32 v[42:43], v[220:221], v[100:101], v[42:43] op_sel:[0,1,0]
	v_pk_fma_f32 v[44:45], v[222:223], v[100:101], v[44:45] op_sel:[0,1,0]
	v_pk_fma_f32 v[38:39], v[220:221], v[104:105], v[38:39] op_sel:[0,1,0]
	v_pk_fma_f32 v[40:41], v[222:223], v[104:105], v[40:41] op_sel:[0,1,0]
	v_pk_fma_f32 v[34:35], v[220:221], v[108:109], v[34:35] op_sel:[0,1,0]
	v_pk_fma_f32 v[36:37], v[222:223], v[108:109], v[36:37] op_sel:[0,1,0]
	v_pk_fma_f32 v[30:31], v[220:221], v[112:113], v[30:31] op_sel:[0,1,0]
	v_pk_fma_f32 v[32:33], v[222:223], v[112:113], v[32:33] op_sel:[0,1,0]
	v_pk_fma_f32 v[26:27], v[220:221], v[116:117], v[26:27] op_sel:[0,1,0]
	v_pk_fma_f32 v[28:29], v[222:223], v[116:117], v[28:29] op_sel:[0,1,0]
	v_pk_fma_f32 v[22:23], v[220:221], v[120:121], v[22:23] op_sel:[0,1,0]
	v_pk_fma_f32 v[24:25], v[222:223], v[120:121], v[24:25] op_sel:[0,1,0]
	v_pk_fma_f32 v[18:19], v[220:221], v[124:125], v[18:19] op_sel:[0,1,0]
	v_pk_fma_f32 v[20:21], v[222:223], v[124:125], v[20:21] op_sel:[0,1,0]
	v_pk_fma_f32 v[14:15], v[220:221], v[128:129], v[14:15] op_sel:[0,1,0]
	v_pk_fma_f32 v[16:17], v[222:223], v[128:129], v[16:17] op_sel:[0,1,0]
	v_pk_fma_f32 v[10:11], v[220:221], v[132:133], v[10:11] op_sel:[0,1,0]
	v_pk_fma_f32 v[12:13], v[222:223], v[132:133], v[12:13] op_sel:[0,1,0]
	v_pk_fma_f32 v[6:7], v[220:221], v[136:137], v[6:7] op_sel:[0,1,0]
	v_pk_fma_f32 v[8:9], v[222:223], v[136:137], v[8:9] op_sel:[0,1,0]
	v_pk_fma_f32 v[2:3], v[220:221], v[140:141], v[2:3] op_sel:[0,1,0]
	v_pk_fma_f32 v[4:5], v[222:223], v[140:141], v[4:5] op_sel:[0,1,0]
	global_load_dwordx4 v[220:223], v[232:233], off
	v_lshl_add_u64 v[232:233], v[232:233], 0, s[0:1]
	s_waitcnt vmcnt(15)
	v_pk_fma_f32 v[64:65], v[226:227], v[82:83], v[64:65] op_sel_hi:[1,0,1]
	v_pk_fma_f32 v[62:63], v[224:225], v[82:83], v[62:63] op_sel_hi:[1,0,1]
	v_pk_fma_f32 v[60:61], v[226:227], v[86:87], v[60:61] op_sel_hi:[1,0,1]
	v_pk_fma_f32 v[58:59], v[224:225], v[86:87], v[58:59] op_sel_hi:[1,0,1]
	v_pk_fma_f32 v[56:57], v[226:227], v[90:91], v[56:57] op_sel_hi:[1,0,1]
	v_pk_fma_f32 v[54:55], v[224:225], v[90:91], v[54:55] op_sel_hi:[1,0,1]
	v_pk_fma_f32 v[52:53], v[226:227], v[94:95], v[52:53] op_sel_hi:[1,0,1]
	v_pk_fma_f32 v[50:51], v[224:225], v[94:95], v[50:51] op_sel_hi:[1,0,1]
	v_pk_fma_f32 v[48:49], v[226:227], v[98:99], v[48:49] op_sel_hi:[1,0,1]
	v_pk_fma_f32 v[46:47], v[224:225], v[98:99], v[46:47] op_sel_hi:[1,0,1]
	v_pk_fma_f32 v[44:45], v[226:227], v[102:103], v[44:45] op_sel_hi:[1,0,1]
	v_pk_fma_f32 v[42:43], v[224:225], v[102:103], v[42:43] op_sel_hi:[1,0,1]
	v_pk_fma_f32 v[40:41], v[226:227], v[106:107], v[40:41] op_sel_hi:[1,0,1]
	v_pk_fma_f32 v[38:39], v[224:225], v[106:107], v[38:39] op_sel_hi:[1,0,1]
	v_pk_fma_f32 v[36:37], v[226:227], v[110:111], v[36:37] op_sel_hi:[1,0,1]
	v_pk_fma_f32 v[34:35], v[224:225], v[110:111], v[34:35] op_sel_hi:[1,0,1]
	v_pk_fma_f32 v[32:33], v[226:227], v[114:115], v[32:33] op_sel_hi:[1,0,1]
	v_pk_fma_f32 v[30:31], v[224:225], v[114:115], v[30:31] op_sel_hi:[1,0,1]
	v_pk_fma_f32 v[28:29], v[226:227], v[118:119], v[28:29] op_sel_hi:[1,0,1]
	v_pk_fma_f32 v[26:27], v[224:225], v[118:119], v[26:27] op_sel_hi:[1,0,1]
	v_pk_fma_f32 v[24:25], v[226:227], v[122:123], v[24:25] op_sel_hi:[1,0,1]
	v_pk_fma_f32 v[22:23], v[224:225], v[122:123], v[22:23] op_sel_hi:[1,0,1]
	v_pk_fma_f32 v[20:21], v[226:227], v[126:127], v[20:21] op_sel_hi:[1,0,1]
	v_pk_fma_f32 v[18:19], v[224:225], v[126:127], v[18:19] op_sel_hi:[1,0,1]
	v_pk_fma_f32 v[16:17], v[226:227], v[130:131], v[16:17] op_sel_hi:[1,0,1]
	v_pk_fma_f32 v[14:15], v[224:225], v[130:131], v[14:15] op_sel_hi:[1,0,1]
	v_pk_fma_f32 v[12:13], v[226:227], v[134:135], v[12:13] op_sel_hi:[1,0,1]
	v_pk_fma_f32 v[10:11], v[224:225], v[134:135], v[10:11] op_sel_hi:[1,0,1]
	v_pk_fma_f32 v[8:9], v[226:227], v[138:139], v[8:9] op_sel_hi:[1,0,1]
	v_pk_fma_f32 v[6:7], v[224:225], v[138:139], v[6:7] op_sel_hi:[1,0,1]
	v_pk_fma_f32 v[4:5], v[226:227], v[142:143], v[4:5] op_sel_hi:[1,0,1]
	v_pk_fma_f32 v[2:3], v[224:225], v[142:143], v[2:3] op_sel_hi:[1,0,1]
	global_load_dwordx4 v[224:227], v[232:233], off
	v_lshl_add_u64 v[232:233], v[232:233], 0, s[0:1]
	s_waitcnt vmcnt(15)
	v_pk_fma_f32 v[64:65], v[230:231], v[68:69], v[64:65] op_sel_hi:[1,0,1]
	v_pk_fma_f32 v[62:63], v[228:229], v[68:69], v[62:63] op_sel_hi:[1,0,1]
	v_pk_fma_f32 v[60:61], v[230:231], v[72:73], v[60:61] op_sel_hi:[1,0,1]
	v_pk_fma_f32 v[58:59], v[228:229], v[72:73], v[58:59] op_sel_hi:[1,0,1]
	v_pk_fma_f32 v[56:57], v[230:231], v[156:157], v[56:57] op_sel_hi:[1,0,1]
	v_pk_fma_f32 v[54:55], v[228:229], v[156:157], v[54:55] op_sel_hi:[1,0,1]
	v_pk_fma_f32 v[52:53], v[230:231], v[158:159], v[52:53] op_sel_hi:[1,0,1]
	v_pk_fma_f32 v[50:51], v[228:229], v[158:159], v[50:51] op_sel_hi:[1,0,1]
	v_pk_fma_f32 v[48:49], v[230:231], v[160:161], v[48:49] op_sel_hi:[1,0,1]
	v_pk_fma_f32 v[46:47], v[228:229], v[160:161], v[46:47] op_sel_hi:[1,0,1]
	v_pk_fma_f32 v[44:45], v[230:231], v[162:163], v[44:45] op_sel_hi:[1,0,1]
	v_pk_fma_f32 v[42:43], v[228:229], v[162:163], v[42:43] op_sel_hi:[1,0,1]
	v_pk_fma_f32 v[40:41], v[230:231], v[164:165], v[40:41] op_sel_hi:[1,0,1]
	v_pk_fma_f32 v[38:39], v[228:229], v[164:165], v[38:39] op_sel_hi:[1,0,1]
	v_pk_fma_f32 v[36:37], v[230:231], v[166:167], v[36:37] op_sel_hi:[1,0,1]
	v_pk_fma_f32 v[34:35], v[228:229], v[166:167], v[34:35] op_sel_hi:[1,0,1]
	v_pk_fma_f32 v[32:33], v[230:231], v[168:169], v[32:33] op_sel_hi:[1,0,1]
	v_pk_fma_f32 v[30:31], v[228:229], v[168:169], v[30:31] op_sel_hi:[1,0,1]
	v_pk_fma_f32 v[28:29], v[230:231], v[170:171], v[28:29] op_sel_hi:[1,0,1]
	v_pk_fma_f32 v[26:27], v[228:229], v[170:171], v[26:27] op_sel_hi:[1,0,1]
	v_pk_fma_f32 v[24:25], v[230:231], v[172:173], v[24:25] op_sel_hi:[1,0,1]
	v_pk_fma_f32 v[22:23], v[228:229], v[172:173], v[22:23] op_sel_hi:[1,0,1]
	v_pk_fma_f32 v[20:21], v[230:231], v[174:175], v[20:21] op_sel_hi:[1,0,1]
	v_pk_fma_f32 v[18:19], v[228:229], v[174:175], v[18:19] op_sel_hi:[1,0,1]
	v_pk_fma_f32 v[16:17], v[230:231], v[176:177], v[16:17] op_sel_hi:[1,0,1]
	v_pk_fma_f32 v[14:15], v[228:229], v[176:177], v[14:15] op_sel_hi:[1,0,1]
	v_pk_fma_f32 v[12:13], v[230:231], v[178:179], v[12:13] op_sel_hi:[1,0,1]
	v_pk_fma_f32 v[10:11], v[228:229], v[178:179], v[10:11] op_sel_hi:[1,0,1]
	v_pk_fma_f32 v[8:9], v[230:231], v[180:181], v[8:9] op_sel_hi:[1,0,1]
	v_pk_fma_f32 v[6:7], v[228:229], v[180:181], v[6:7] op_sel_hi:[1,0,1]
	v_pk_fma_f32 v[4:5], v[230:231], v[182:183], v[4:5] op_sel_hi:[1,0,1]
	v_pk_fma_f32 v[2:3], v[228:229], v[182:183], v[2:3] op_sel_hi:[1,0,1]
	global_load_dwordx4 v[228:231], v[232:233], off
	v_lshl_add_u64 v[232:233], v[232:233], 0, s[0:1]
	s_add_i32 s8, s8, 1
	s_cmp_eq_u32 s8, 7
	s_cbranch_scc0 .Lada_loop
	v_mov_b32_e32 v68, s10
	ds_read_b128 v[80:83], v68
	ds_read_b128 v[84:87], v68 offset:4096
	ds_read_b128 v[88:91], v68 offset:8192
	ds_read_b128 v[92:95], v68 offset:12288
	ds_read_b128 v[96:99], v68 offset:16384
	ds_read_b128 v[100:103], v68 offset:20480
	ds_read_b128 v[104:107], v68 offset:24576
	ds_read_b128 v[108:111], v68 offset:28672
	ds_read_b128 v[112:115], v68 offset:32768
	ds_read_b128 v[116:119], v68 offset:36864
	ds_read_b128 v[120:123], v68 offset:40960
	ds_read_b128 v[124:127], v68 offset:45056
	ds_read_b128 v[128:131], v68 offset:49152
	ds_read_b128 v[132:135], v68 offset:53248
	ds_read_b128 v[136:139], v68 offset:57344
	ds_read_b128 v[140:143], v68 offset:61440
	s_add_i32 s10, s10, 16
	s_waitcnt lgkmcnt(14)
	v_mov_b32_e32 v68, v83
	v_mov_b32_e32 v72, v87
	s_waitcnt lgkmcnt(13)
	v_mov_b32_e32 v156, v91
	s_waitcnt lgkmcnt(12)
	v_mov_b32_e32 v158, v95
	s_waitcnt lgkmcnt(11)
	v_mov_b32_e32 v160, v99
	s_waitcnt lgkmcnt(10)
	v_mov_b32_e32 v162, v103
	s_waitcnt lgkmcnt(9)
	v_mov_b32_e32 v164, v107
	s_waitcnt lgkmcnt(8)
	v_mov_b32_e32 v166, v111
	s_waitcnt lgkmcnt(7)
	v_mov_b32_e32 v168, v115
	s_waitcnt lgkmcnt(6)
	v_mov_b32_e32 v170, v119
	s_waitcnt lgkmcnt(5)
	v_mov_b32_e32 v172, v123
	s_waitcnt lgkmcnt(4)
	v_mov_b32_e32 v174, v127
	s_waitcnt lgkmcnt(3)
	v_mov_b32_e32 v176, v131
	s_waitcnt lgkmcnt(2)
	v_mov_b32_e32 v178, v135
	s_waitcnt lgkmcnt(1)
	v_mov_b32_e32 v180, v139
	s_waitcnt lgkmcnt(0)
	v_mov_b32_e32 v182, v143
	s_waitcnt vmcnt(15)
	v_pk_fma_f32 v[64:65], v[78:79], v[80:81], v[64:65] op_sel_hi:[1,0,1]
	v_pk_fma_f32 v[62:63], v[76:77], v[80:81], v[62:63] op_sel_hi:[1,0,1]
	v_pk_fma_f32 v[60:61], v[78:79], v[84:85], v[60:61] op_sel_hi:[1,0,1]
	v_pk_fma_f32 v[58:59], v[76:77], v[84:85], v[58:59] op_sel_hi:[1,0,1]
	v_pk_fma_f32 v[56:57], v[78:79], v[88:89], v[56:57] op_sel_hi:[1,0,1]
	v_pk_fma_f32 v[54:55], v[76:77], v[88:89], v[54:55] op_sel_hi:[1,0,1]
	v_pk_fma_f32 v[52:53], v[78:79], v[92:93], v[52:53] op_sel_hi:[1,0,1]
	v_pk_fma_f32 v[50:51], v[76:77], v[92:93], v[50:51] op_sel_hi:[1,0,1]
	v_pk_fma_f32 v[48:49], v[78:79], v[96:97], v[48:49] op_sel_hi:[1,0,1]
	v_pk_fma_f32 v[46:47], v[76:77], v[96:97], v[46:47] op_sel_hi:[1,0,1]
	v_pk_fma_f32 v[44:45], v[78:79], v[100:101], v[44:45] op_sel_hi:[1,0,1]
	v_pk_fma_f32 v[42:43], v[76:77], v[100:101], v[42:43] op_sel_hi:[1,0,1]
	v_pk_fma_f32 v[40:41], v[78:79], v[104:105], v[40:41] op_sel_hi:[1,0,1]
	v_pk_fma_f32 v[38:39], v[76:77], v[104:105], v[38:39] op_sel_hi:[1,0,1]
	v_pk_fma_f32 v[36:37], v[78:79], v[108:109], v[36:37] op_sel_hi:[1,0,1]
	v_pk_fma_f32 v[34:35], v[76:77], v[108:109], v[34:35] op_sel_hi:[1,0,1]
	v_pk_fma_f32 v[32:33], v[78:79], v[112:113], v[32:33] op_sel_hi:[1,0,1]
	v_pk_fma_f32 v[30:31], v[76:77], v[112:113], v[30:31] op_sel_hi:[1,0,1]
	v_pk_fma_f32 v[28:29], v[78:79], v[116:117], v[28:29] op_sel_hi:[1,0,1]
	v_pk_fma_f32 v[26:27], v[76:77], v[116:117], v[26:27] op_sel_hi:[1,0,1]
	v_pk_fma_f32 v[24:25], v[78:79], v[120:121], v[24:25] op_sel_hi:[1,0,1]
	v_pk_fma_f32 v[22:23], v[76:77], v[120:121], v[22:23] op_sel_hi:[1,0,1]
	v_pk_fma_f32 v[20:21], v[78:79], v[124:125], v[20:21] op_sel_hi:[1,0,1]
	v_pk_fma_f32 v[18:19], v[76:77], v[124:125], v[18:19] op_sel_hi:[1,0,1]
	v_pk_fma_f32 v[16:17], v[78:79], v[128:129], v[16:17] op_sel_hi:[1,0,1]
	v_pk_fma_f32 v[14:15], v[76:77], v[128:129], v[14:15] op_sel_hi:[1,0,1]
	v_pk_fma_f32 v[12:13], v[78:79], v[132:133], v[12:13] op_sel_hi:[1,0,1]
	v_pk_fma_f32 v[10:11], v[76:77], v[132:133], v[10:11] op_sel_hi:[1,0,1]
	v_pk_fma_f32 v[8:9], v[78:79], v[136:137], v[8:9] op_sel_hi:[1,0,1]
	v_pk_fma_f32 v[6:7], v[76:77], v[136:137], v[6:7] op_sel_hi:[1,0,1]
	v_pk_fma_f32 v[4:5], v[78:79], v[140:141], v[4:5] op_sel_hi:[1,0,1]
	v_pk_fma_f32 v[2:3], v[76:77], v[140:141], v[2:3] op_sel_hi:[1,0,1]
	s_waitcnt vmcnt(14)
	v_pk_fma_f32 v[62:63], v[144:145], v[80:81], v[62:63] op_sel:[0,1,0]
	v_pk_fma_f32 v[64:65], v[146:147], v[80:81], v[64:65] op_sel:[0,1,0]
	v_pk_fma_f32 v[58:59], v[144:145], v[84:85], v[58:59] op_sel:[0,1,0]
	v_pk_fma_f32 v[60:61], v[146:147], v[84:85], v[60:61] op_sel:[0,1,0]
	v_pk_fma_f32 v[54:55], v[144:145], v[88:89], v[54:55] op_sel:[0,1,0]
	v_pk_fma_f32 v[56:57], v[146:147], v[88:89], v[56:57] op_sel:[0,1,0]
	v_pk_fma_f32 v[50:51], v[144:145], v[92:93], v[50:51] op_sel:[0,1,0]
	v_pk_fma_f32 v[52:53], v[146:147], v[92:93], v[52:53] op_sel:[0,1,0]
	v_pk_fma_f32 v[46:47], v[144:145], v[96:97], v[46:47] op_sel:[0,1,0]
	v_pk_fma_f32 v[48:49], v[146:147], v[96:97], v[48:49] op_sel:[0,1,0]
	v_pk_fma_f32 v[42:43], v[144:145], v[100:101], v[42:43] op_sel:[0,1,0]
	v_pk_fma_f32 v[44:45], v[146:147], v[100:101], v[44:45] op_sel:[0,1,0]
	v_pk_fma_f32 v[38:39], v[144:145], v[104:105], v[38:39] op_sel:[0,1,0]
	v_pk_fma_f32 v[40:41], v[146:147], v[104:105], v[40:41] op_sel:[0,1,0]
	v_pk_fma_f32 v[34:35], v[144:145], v[108:109], v[34:35] op_sel:[0,1,0]
	v_pk_fma_f32 v[36:37], v[146:147], v[108:109], v[36:37] op_sel:[0,1,0]
	v_pk_fma_f32 v[30:31], v[144:145], v[112:113], v[30:31] op_sel:[0,1,0]
	v_pk_fma_f32 v[32:33], v[146:147], v[112:113], v[32:33] op_sel:[0,1,0]
	v_pk_fma_f32 v[26:27], v[144:145], v[116:117], v[26:27] op_sel:[0,1,0]
	v_pk_fma_f32 v[28:29], v[146:147], v[116:117], v[28:29] op_sel:[0,1,0]
	v_pk_fma_f32 v[22:23], v[144:145], v[120:121], v[22:23] op_sel:[0,1,0]
	v_pk_fma_f32 v[24:25], v[146:147], v[120:121], v[24:25] op_sel:[0,1,0]
	v_pk_fma_f32 v[18:19], v[144:145], v[124:125], v[18:19] op_sel:[0,1,0]
	v_pk_fma_f32 v[20:21], v[146:147], v[124:125], v[20:21] op_sel:[0,1,0]
	v_pk_fma_f32 v[14:15], v[144:145], v[128:129], v[14:15] op_sel:[0,1,0]
	v_pk_fma_f32 v[16:17], v[146:147], v[128:129], v[16:17] op_sel:[0,1,0]
	v_pk_fma_f32 v[10:11], v[144:145], v[132:133], v[10:11] op_sel:[0,1,0]
	v_pk_fma_f32 v[12:13], v[146:147], v[132:133], v[12:13] op_sel:[0,1,0]
	v_pk_fma_f32 v[6:7], v[144:145], v[136:137], v[6:7] op_sel:[0,1,0]
	v_pk_fma_f32 v[8:9], v[146:147], v[136:137], v[8:9] op_sel:[0,1,0]
	v_pk_fma_f32 v[2:3], v[144:145], v[140:141], v[2:3] op_sel:[0,1,0]
	v_pk_fma_f32 v[4:5], v[146:147], v[140:141], v[4:5] op_sel:[0,1,0]
	s_waitcnt vmcnt(13)
	v_pk_fma_f32 v[64:65], v[150:151], v[82:83], v[64:65] op_sel_hi:[1,0,1]
	v_pk_fma_f32 v[62:63], v[148:149], v[82:83], v[62:63] op_sel_hi:[1,0,1]
	v_pk_fma_f32 v[60:61], v[150:151], v[86:87], v[60:61] op_sel_hi:[1,0,1]
	v_pk_fma_f32 v[58:59], v[148:149], v[86:87], v[58:59] op_sel_hi:[1,0,1]
	v_pk_fma_f32 v[56:57], v[150:151], v[90:91], v[56:57] op_sel_hi:[1,0,1]
	v_pk_fma_f32 v[54:55], v[148:149], v[90:91], v[54:55] op_sel_hi:[1,0,1]
	v_pk_fma_f32 v[52:53], v[150:151], v[94:95], v[52:53] op_sel_hi:[1,0,1]
	v_pk_fma_f32 v[50:51], v[148:149], v[94:95], v[50:51] op_sel_hi:[1,0,1]
	v_pk_fma_f32 v[48:49], v[150:151], v[98:99], v[48:49] op_sel_hi:[1,0,1]
	v_pk_fma_f32 v[46:47], v[148:149], v[98:99], v[46:47] op_sel_hi:[1,0,1]
	v_pk_fma_f32 v[44:45], v[150:151], v[102:103], v[44:45] op_sel_hi:[1,0,1]
	v_pk_fma_f32 v[42:43], v[148:149], v[102:103], v[42:43] op_sel_hi:[1,0,1]
	v_pk_fma_f32 v[40:41], v[150:151], v[106:107], v[40:41] op_sel_hi:[1,0,1]
	v_pk_fma_f32 v[38:39], v[148:149], v[106:107], v[38:39] op_sel_hi:[1,0,1]
	v_pk_fma_f32 v[36:37], v[150:151], v[110:111], v[36:37] op_sel_hi:[1,0,1]
	v_pk_fma_f32 v[34:35], v[148:149], v[110:111], v[34:35] op_sel_hi:[1,0,1]
	v_pk_fma_f32 v[32:33], v[150:151], v[114:115], v[32:33] op_sel_hi:[1,0,1]
	v_pk_fma_f32 v[30:31], v[148:149], v[114:115], v[30:31] op_sel_hi:[1,0,1]
	v_pk_fma_f32 v[28:29], v[150:151], v[118:119], v[28:29] op_sel_hi:[1,0,1]
	v_pk_fma_f32 v[26:27], v[148:149], v[118:119], v[26:27] op_sel_hi:[1,0,1]
	v_pk_fma_f32 v[24:25], v[150:151], v[122:123], v[24:25] op_sel_hi:[1,0,1]
	v_pk_fma_f32 v[22:23], v[148:149], v[122:123], v[22:23] op_sel_hi:[1,0,1]
	v_pk_fma_f32 v[20:21], v[150:151], v[126:127], v[20:21] op_sel_hi:[1,0,1]
	v_pk_fma_f32 v[18:19], v[148:149], v[126:127], v[18:19] op_sel_hi:[1,0,1]
	v_pk_fma_f32 v[16:17], v[150:151], v[130:131], v[16:17] op_sel_hi:[1,0,1]
	v_pk_fma_f32 v[14:15], v[148:149], v[130:131], v[14:15] op_sel_hi:[1,0,1]
	v_pk_fma_f32 v[12:13], v[150:151], v[134:135], v[12:13] op_sel_hi:[1,0,1]
	v_pk_fma_f32 v[10:11], v[148:149], v[134:135], v[10:11] op_sel_hi:[1,0,1]
	v_pk_fma_f32 v[8:9], v[150:151], v[138:139], v[8:9] op_sel_hi:[1,0,1]
	v_pk_fma_f32 v[6:7], v[148:149], v[138:139], v[6:7] op_sel_hi:[1,0,1]
	v_pk_fma_f32 v[4:5], v[150:151], v[142:143], v[4:5] op_sel_hi:[1,0,1]
	v_pk_fma_f32 v[2:3], v[148:149], v[142:143], v[2:3] op_sel_hi:[1,0,1]
	s_waitcnt vmcnt(12)
	v_pk_fma_f32 v[64:65], v[154:155], v[68:69], v[64:65] op_sel_hi:[1,0,1]
	v_pk_fma_f32 v[62:63], v[152:153], v[68:69], v[62:63] op_sel_hi:[1,0,1]
	v_pk_fma_f32 v[60:61], v[154:155], v[72:73], v[60:61] op_sel_hi:[1,0,1]
	v_pk_fma_f32 v[58:59], v[152:153], v[72:73], v[58:59] op_sel_hi:[1,0,1]
	v_pk_fma_f32 v[56:57], v[154:155], v[156:157], v[56:57] op_sel_hi:[1,0,1]
	v_pk_fma_f32 v[54:55], v[152:153], v[156:157], v[54:55] op_sel_hi:[1,0,1]
	v_pk_fma_f32 v[52:53], v[154:155], v[158:159], v[52:53] op_sel_hi:[1,0,1]
	v_pk_fma_f32 v[50:51], v[152:153], v[158:159], v[50:51] op_sel_hi:[1,0,1]
	v_pk_fma_f32 v[48:49], v[154:155], v[160:161], v[48:49] op_sel_hi:[1,0,1]
	v_pk_fma_f32 v[46:47], v[152:153], v[160:161], v[46:47] op_sel_hi:[1,0,1]
	v_pk_fma_f32 v[44:45], v[154:155], v[162:163], v[44:45] op_sel_hi:[1,0,1]
	v_pk_fma_f32 v[42:43], v[152:153], v[162:163], v[42:43] op_sel_hi:[1,0,1]
	v_pk_fma_f32 v[40:41], v[154:155], v[164:165], v[40:41] op_sel_hi:[1,0,1]
	v_pk_fma_f32 v[38:39], v[152:153], v[164:165], v[38:39] op_sel_hi:[1,0,1]
	v_pk_fma_f32 v[36:37], v[154:155], v[166:167], v[36:37] op_sel_hi:[1,0,1]
	v_pk_fma_f32 v[34:35], v[152:153], v[166:167], v[34:35] op_sel_hi:[1,0,1]
	v_pk_fma_f32 v[32:33], v[154:155], v[168:169], v[32:33] op_sel_hi:[1,0,1]
	v_pk_fma_f32 v[30:31], v[152:153], v[168:169], v[30:31] op_sel_hi:[1,0,1]
	v_pk_fma_f32 v[28:29], v[154:155], v[170:171], v[28:29] op_sel_hi:[1,0,1]
	v_pk_fma_f32 v[26:27], v[152:153], v[170:171], v[26:27] op_sel_hi:[1,0,1]
	v_pk_fma_f32 v[24:25], v[154:155], v[172:173], v[24:25] op_sel_hi:[1,0,1]
	v_pk_fma_f32 v[22:23], v[152:153], v[172:173], v[22:23] op_sel_hi:[1,0,1]
	v_pk_fma_f32 v[20:21], v[154:155], v[174:175], v[20:21] op_sel_hi:[1,0,1]
	v_pk_fma_f32 v[18:19], v[152:153], v[174:175], v[18:19] op_sel_hi:[1,0,1]
	v_pk_fma_f32 v[16:17], v[154:155], v[176:177], v[16:17] op_sel_hi:[1,0,1]
	v_pk_fma_f32 v[14:15], v[152:153], v[176:177], v[14:15] op_sel_hi:[1,0,1]
	v_pk_fma_f32 v[12:13], v[154:155], v[178:179], v[12:13] op_sel_hi:[1,0,1]
	v_pk_fma_f32 v[10:11], v[152:153], v[178:179], v[10:11] op_sel_hi:[1,0,1]
	v_pk_fma_f32 v[8:9], v[154:155], v[180:181], v[8:9] op_sel_hi:[1,0,1]
	v_pk_fma_f32 v[6:7], v[152:153], v[180:181], v[6:7] op_sel_hi:[1,0,1]
	v_pk_fma_f32 v[4:5], v[154:155], v[182:183], v[4:5] op_sel_hi:[1,0,1]
	v_pk_fma_f32 v[2:3], v[152:153], v[182:183], v[2:3] op_sel_hi:[1,0,1]
	v_mov_b32_e32 v68, s10
	ds_read_b128 v[80:83], v68
	ds_read_b128 v[84:87], v68 offset:4096
	ds_read_b128 v[88:91], v68 offset:8192
	ds_read_b128 v[92:95], v68 offset:12288
	ds_read_b128 v[96:99], v68 offset:16384
	ds_read_b128 v[100:103], v68 offset:20480
	ds_read_b128 v[104:107], v68 offset:24576
	ds_read_b128 v[108:111], v68 offset:28672
	ds_read_b128 v[112:115], v68 offset:32768
	ds_read_b128 v[116:119], v68 offset:36864
	ds_read_b128 v[120:123], v68 offset:40960
	ds_read_b128 v[124:127], v68 offset:45056
	ds_read_b128 v[128:131], v68 offset:49152
	ds_read_b128 v[132:135], v68 offset:53248
	ds_read_b128 v[136:139], v68 offset:57344
	ds_read_b128 v[140:143], v68 offset:61440
	s_add_i32 s10, s10, 16
	s_waitcnt lgkmcnt(14)
	v_mov_b32_e32 v68, v83
	v_mov_b32_e32 v72, v87
	s_waitcnt lgkmcnt(13)
	v_mov_b32_e32 v156, v91
	s_waitcnt lgkmcnt(12)
	v_mov_b32_e32 v158, v95
	s_waitcnt lgkmcnt(11)
	v_mov_b32_e32 v160, v99
	s_waitcnt lgkmcnt(10)
	v_mov_b32_e32 v162, v103
	s_waitcnt lgkmcnt(9)
	v_mov_b32_e32 v164, v107
	s_waitcnt lgkmcnt(8)
	v_mov_b32_e32 v166, v111
	s_waitcnt lgkmcnt(7)
	v_mov_b32_e32 v168, v115
	s_waitcnt lgkmcnt(6)
	v_mov_b32_e32 v170, v119
	s_waitcnt lgkmcnt(5)
	v_mov_b32_e32 v172, v123
	s_waitcnt lgkmcnt(4)
	v_mov_b32_e32 v174, v127
	s_waitcnt lgkmcnt(3)
	v_mov_b32_e32 v176, v131
	s_waitcnt lgkmcnt(2)
	v_mov_b32_e32 v178, v135
	s_waitcnt lgkmcnt(1)
	v_mov_b32_e32 v180, v139
	s_waitcnt lgkmcnt(0)
	v_mov_b32_e32 v182, v143
	s_waitcnt vmcnt(11)
	v_pk_fma_f32 v[64:65], v[186:187], v[80:81], v[64:65] op_sel_hi:[1,0,1]
	v_pk_fma_f32 v[62:63], v[184:185], v[80:81], v[62:63] op_sel_hi:[1,0,1]
	v_pk_fma_f32 v[60:61], v[186:187], v[84:85], v[60:61] op_sel_hi:[1,0,1]
	v_pk_fma_f32 v[58:59], v[184:185], v[84:85], v[58:59] op_sel_hi:[1,0,1]
	v_pk_fma_f32 v[56:57], v[186:187], v[88:89], v[56:57] op_sel_hi:[1,0,1]
	v_pk_fma_f32 v[54:55], v[184:185], v[88:89], v[54:55] op_sel_hi:[1,0,1]
	v_pk_fma_f32 v[52:53], v[186:187], v[92:93], v[52:53] op_sel_hi:[1,0,1]
	v_pk_fma_f32 v[50:51], v[184:185], v[92:93], v[50:51] op_sel_hi:[1,0,1]
	v_pk_fma_f32 v[48:49], v[186:187], v[96:97], v[48:49] op_sel_hi:[1,0,1]
	v_pk_fma_f32 v[46:47], v[184:185], v[96:97], v[46:47] op_sel_hi:[1,0,1]
	v_pk_fma_f32 v[44:45], v[186:187], v[100:101], v[44:45] op_sel_hi:[1,0,1]
	v_pk_fma_f32 v[42:43], v[184:185], v[100:101], v[42:43] op_sel_hi:[1,0,1]
	v_pk_fma_f32 v[40:41], v[186:187], v[104:105], v[40:41] op_sel_hi:[1,0,1]
	v_pk_fma_f32 v[38:39], v[184:185], v[104:105], v[38:39] op_sel_hi:[1,0,1]
	v_pk_fma_f32 v[36:37], v[186:187], v[108:109], v[36:37] op_sel_hi:[1,0,1]
	v_pk_fma_f32 v[34:35], v[184:185], v[108:109], v[34:35] op_sel_hi:[1,0,1]
	v_pk_fma_f32 v[32:33], v[186:187], v[112:113], v[32:33] op_sel_hi:[1,0,1]
	v_pk_fma_f32 v[30:31], v[184:185], v[112:113], v[30:31] op_sel_hi:[1,0,1]
	v_pk_fma_f32 v[28:29], v[186:187], v[116:117], v[28:29] op_sel_hi:[1,0,1]
	v_pk_fma_f32 v[26:27], v[184:185], v[116:117], v[26:27] op_sel_hi:[1,0,1]
	v_pk_fma_f32 v[24:25], v[186:187], v[120:121], v[24:25] op_sel_hi:[1,0,1]
	v_pk_fma_f32 v[22:23], v[184:185], v[120:121], v[22:23] op_sel_hi:[1,0,1]
	v_pk_fma_f32 v[20:21], v[186:187], v[124:125], v[20:21] op_sel_hi:[1,0,1]
	v_pk_fma_f32 v[18:19], v[184:185], v[124:125], v[18:19] op_sel_hi:[1,0,1]
	v_pk_fma_f32 v[16:17], v[186:187], v[128:129], v[16:17] op_sel_hi:[1,0,1]
	v_pk_fma_f32 v[14:15], v[184:185], v[128:129], v[14:15] op_sel_hi:[1,0,1]
	v_pk_fma_f32 v[12:13], v[186:187], v[132:133], v[12:13] op_sel_hi:[1,0,1]
	v_pk_fma_f32 v[10:11], v[184:185], v[132:133], v[10:11] op_sel_hi:[1,0,1]
	v_pk_fma_f32 v[8:9], v[186:187], v[136:137], v[8:9] op_sel_hi:[1,0,1]
	v_pk_fma_f32 v[6:7], v[184:185], v[136:137], v[6:7] op_sel_hi:[1,0,1]
	v_pk_fma_f32 v[4:5], v[186:187], v[140:141], v[4:5] op_sel_hi:[1,0,1]
	v_pk_fma_f32 v[2:3], v[184:185], v[140:141], v[2:3] op_sel_hi:[1,0,1]
	s_waitcnt vmcnt(10)
	v_pk_fma_f32 v[62:63], v[188:189], v[80:81], v[62:63] op_sel:[0,1,0]
	v_pk_fma_f32 v[64:65], v[190:191], v[80:81], v[64:65] op_sel:[0,1,0]
	v_pk_fma_f32 v[58:59], v[188:189], v[84:85], v[58:59] op_sel:[0,1,0]
	v_pk_fma_f32 v[60:61], v[190:191], v[84:85], v[60:61] op_sel:[0,1,0]
	v_pk_fma_f32 v[54:55], v[188:189], v[88:89], v[54:55] op_sel:[0,1,0]
	v_pk_fma_f32 v[56:57], v[190:191], v[88:89], v[56:57] op_sel:[0,1,0]
	v_pk_fma_f32 v[50:51], v[188:189], v[92:93], v[50:51] op_sel:[0,1,0]
	v_pk_fma_f32 v[52:53], v[190:191], v[92:93], v[52:53] op_sel:[0,1,0]
	v_pk_fma_f32 v[46:47], v[188:189], v[96:97], v[46:47] op_sel:[0,1,0]
	v_pk_fma_f32 v[48:49], v[190:191], v[96:97], v[48:49] op_sel:[0,1,0]
	v_pk_fma_f32 v[42:43], v[188:189], v[100:101], v[42:43] op_sel:[0,1,0]
	v_pk_fma_f32 v[44:45], v[190:191], v[100:101], v[44:45] op_sel:[0,1,0]
	v_pk_fma_f32 v[38:39], v[188:189], v[104:105], v[38:39] op_sel:[0,1,0]
	v_pk_fma_f32 v[40:41], v[190:191], v[104:105], v[40:41] op_sel:[0,1,0]
	v_pk_fma_f32 v[34:35], v[188:189], v[108:109], v[34:35] op_sel:[0,1,0]
	v_pk_fma_f32 v[36:37], v[190:191], v[108:109], v[36:37] op_sel:[0,1,0]
	v_pk_fma_f32 v[30:31], v[188:189], v[112:113], v[30:31] op_sel:[0,1,0]
	v_pk_fma_f32 v[32:33], v[190:191], v[112:113], v[32:33] op_sel:[0,1,0]
	v_pk_fma_f32 v[26:27], v[188:189], v[116:117], v[26:27] op_sel:[0,1,0]
	v_pk_fma_f32 v[28:29], v[190:191], v[116:117], v[28:29] op_sel:[0,1,0]
	v_pk_fma_f32 v[22:23], v[188:189], v[120:121], v[22:23] op_sel:[0,1,0]
	v_pk_fma_f32 v[24:25], v[190:191], v[120:121], v[24:25] op_sel:[0,1,0]
	v_pk_fma_f32 v[18:19], v[188:189], v[124:125], v[18:19] op_sel:[0,1,0]
	v_pk_fma_f32 v[20:21], v[190:191], v[124:125], v[20:21] op_sel:[0,1,0]
	v_pk_fma_f32 v[14:15], v[188:189], v[128:129], v[14:15] op_sel:[0,1,0]
	v_pk_fma_f32 v[16:17], v[190:191], v[128:129], v[16:17] op_sel:[0,1,0]
	v_pk_fma_f32 v[10:11], v[188:189], v[132:133], v[10:11] op_sel:[0,1,0]
	v_pk_fma_f32 v[12:13], v[190:191], v[132:133], v[12:13] op_sel:[0,1,0]
	v_pk_fma_f32 v[6:7], v[188:189], v[136:137], v[6:7] op_sel:[0,1,0]
	v_pk_fma_f32 v[8:9], v[190:191], v[136:137], v[8:9] op_sel:[0,1,0]
	v_pk_fma_f32 v[2:3], v[188:189], v[140:141], v[2:3] op_sel:[0,1,0]
	v_pk_fma_f32 v[4:5], v[190:191], v[140:141], v[4:5] op_sel:[0,1,0]
	s_waitcnt vmcnt(9)
	v_pk_fma_f32 v[64:65], v[194:195], v[82:83], v[64:65] op_sel_hi:[1,0,1]
	v_pk_fma_f32 v[62:63], v[192:193], v[82:83], v[62:63] op_sel_hi:[1,0,1]
	v_pk_fma_f32 v[60:61], v[194:195], v[86:87], v[60:61] op_sel_hi:[1,0,1]
	v_pk_fma_f32 v[58:59], v[192:193], v[86:87], v[58:59] op_sel_hi:[1,0,1]
	v_pk_fma_f32 v[56:57], v[194:195], v[90:91], v[56:57] op_sel_hi:[1,0,1]
	v_pk_fma_f32 v[54:55], v[192:193], v[90:91], v[54:55] op_sel_hi:[1,0,1]
	v_pk_fma_f32 v[52:53], v[194:195], v[94:95], v[52:53] op_sel_hi:[1,0,1]
	v_pk_fma_f32 v[50:51], v[192:193], v[94:95], v[50:51] op_sel_hi:[1,0,1]
	v_pk_fma_f32 v[48:49], v[194:195], v[98:99], v[48:49] op_sel_hi:[1,0,1]
	v_pk_fma_f32 v[46:47], v[192:193], v[98:99], v[46:47] op_sel_hi:[1,0,1]
	v_pk_fma_f32 v[44:45], v[194:195], v[102:103], v[44:45] op_sel_hi:[1,0,1]
	v_pk_fma_f32 v[42:43], v[192:193], v[102:103], v[42:43] op_sel_hi:[1,0,1]
	v_pk_fma_f32 v[40:41], v[194:195], v[106:107], v[40:41] op_sel_hi:[1,0,1]
	v_pk_fma_f32 v[38:39], v[192:193], v[106:107], v[38:39] op_sel_hi:[1,0,1]
	v_pk_fma_f32 v[36:37], v[194:195], v[110:111], v[36:37] op_sel_hi:[1,0,1]
	v_pk_fma_f32 v[34:35], v[192:193], v[110:111], v[34:35] op_sel_hi:[1,0,1]
	v_pk_fma_f32 v[32:33], v[194:195], v[114:115], v[32:33] op_sel_hi:[1,0,1]
	v_pk_fma_f32 v[30:31], v[192:193], v[114:115], v[30:31] op_sel_hi:[1,0,1]
	v_pk_fma_f32 v[28:29], v[194:195], v[118:119], v[28:29] op_sel_hi:[1,0,1]
	v_pk_fma_f32 v[26:27], v[192:193], v[118:119], v[26:27] op_sel_hi:[1,0,1]
	v_pk_fma_f32 v[24:25], v[194:195], v[122:123], v[24:25] op_sel_hi:[1,0,1]
	v_pk_fma_f32 v[22:23], v[192:193], v[122:123], v[22:23] op_sel_hi:[1,0,1]
	v_pk_fma_f32 v[20:21], v[194:195], v[126:127], v[20:21] op_sel_hi:[1,0,1]
	v_pk_fma_f32 v[18:19], v[192:193], v[126:127], v[18:19] op_sel_hi:[1,0,1]
	v_pk_fma_f32 v[16:17], v[194:195], v[130:131], v[16:17] op_sel_hi:[1,0,1]
	v_pk_fma_f32 v[14:15], v[192:193], v[130:131], v[14:15] op_sel_hi:[1,0,1]
	v_pk_fma_f32 v[12:13], v[194:195], v[134:135], v[12:13] op_sel_hi:[1,0,1]
	v_pk_fma_f32 v[10:11], v[192:193], v[134:135], v[10:11] op_sel_hi:[1,0,1]
	v_pk_fma_f32 v[8:9], v[194:195], v[138:139], v[8:9] op_sel_hi:[1,0,1]
	v_pk_fma_f32 v[6:7], v[192:193], v[138:139], v[6:7] op_sel_hi:[1,0,1]
	v_pk_fma_f32 v[4:5], v[194:195], v[142:143], v[4:5] op_sel_hi:[1,0,1]
	v_pk_fma_f32 v[2:3], v[192:193], v[142:143], v[2:3] op_sel_hi:[1,0,1]
	s_waitcnt vmcnt(8)
	v_pk_fma_f32 v[64:65], v[198:199], v[68:69], v[64:65] op_sel_hi:[1,0,1]
	v_pk_fma_f32 v[62:63], v[196:197], v[68:69], v[62:63] op_sel_hi:[1,0,1]
	v_pk_fma_f32 v[60:61], v[198:199], v[72:73], v[60:61] op_sel_hi:[1,0,1]
	v_pk_fma_f32 v[58:59], v[196:197], v[72:73], v[58:59] op_sel_hi:[1,0,1]
	v_pk_fma_f32 v[56:57], v[198:199], v[156:157], v[56:57] op_sel_hi:[1,0,1]
	v_pk_fma_f32 v[54:55], v[196:197], v[156:157], v[54:55] op_sel_hi:[1,0,1]
	v_pk_fma_f32 v[52:53], v[198:199], v[158:159], v[52:53] op_sel_hi:[1,0,1]
	v_pk_fma_f32 v[50:51], v[196:197], v[158:159], v[50:51] op_sel_hi:[1,0,1]
	v_pk_fma_f32 v[48:49], v[198:199], v[160:161], v[48:49] op_sel_hi:[1,0,1]
	v_pk_fma_f32 v[46:47], v[196:197], v[160:161], v[46:47] op_sel_hi:[1,0,1]
	v_pk_fma_f32 v[44:45], v[198:199], v[162:163], v[44:45] op_sel_hi:[1,0,1]
	v_pk_fma_f32 v[42:43], v[196:197], v[162:163], v[42:43] op_sel_hi:[1,0,1]
	v_pk_fma_f32 v[40:41], v[198:199], v[164:165], v[40:41] op_sel_hi:[1,0,1]
	v_pk_fma_f32 v[38:39], v[196:197], v[164:165], v[38:39] op_sel_hi:[1,0,1]
	v_pk_fma_f32 v[36:37], v[198:199], v[166:167], v[36:37] op_sel_hi:[1,0,1]
	v_pk_fma_f32 v[34:35], v[196:197], v[166:167], v[34:35] op_sel_hi:[1,0,1]
	v_pk_fma_f32 v[32:33], v[198:199], v[168:169], v[32:33] op_sel_hi:[1,0,1]
	v_pk_fma_f32 v[30:31], v[196:197], v[168:169], v[30:31] op_sel_hi:[1,0,1]
	v_pk_fma_f32 v[28:29], v[198:199], v[170:171], v[28:29] op_sel_hi:[1,0,1]
	v_pk_fma_f32 v[26:27], v[196:197], v[170:171], v[26:27] op_sel_hi:[1,0,1]
	v_pk_fma_f32 v[24:25], v[198:199], v[172:173], v[24:25] op_sel_hi:[1,0,1]
	v_pk_fma_f32 v[22:23], v[196:197], v[172:173], v[22:23] op_sel_hi:[1,0,1]
	v_pk_fma_f32 v[20:21], v[198:199], v[174:175], v[20:21] op_sel_hi:[1,0,1]
	v_pk_fma_f32 v[18:19], v[196:197], v[174:175], v[18:19] op_sel_hi:[1,0,1]
	v_pk_fma_f32 v[16:17], v[198:199], v[176:177], v[16:17] op_sel_hi:[1,0,1]
	v_pk_fma_f32 v[14:15], v[196:197], v[176:177], v[14:15] op_sel_hi:[1,0,1]
	v_pk_fma_f32 v[12:13], v[198:199], v[178:179], v[12:13] op_sel_hi:[1,0,1]
	v_pk_fma_f32 v[10:11], v[196:197], v[178:179], v[10:11] op_sel_hi:[1,0,1]
	v_pk_fma_f32 v[8:9], v[198:199], v[180:181], v[8:9] op_sel_hi:[1,0,1]
	v_pk_fma_f32 v[6:7], v[196:197], v[180:181], v[6:7] op_sel_hi:[1,0,1]
	v_pk_fma_f32 v[4:5], v[198:199], v[182:183], v[4:5] op_sel_hi:[1,0,1]
	v_pk_fma_f32 v[2:3], v[196:197], v[182:183], v[2:3] op_sel_hi:[1,0,1]
	v_mov_b32_e32 v68, s10
	ds_read_b128 v[80:83], v68
	ds_read_b128 v[84:87], v68 offset:4096
	ds_read_b128 v[88:91], v68 offset:8192
	ds_read_b128 v[92:95], v68 offset:12288
	ds_read_b128 v[96:99], v68 offset:16384
	ds_read_b128 v[100:103], v68 offset:20480
	ds_read_b128 v[104:107], v68 offset:24576
	ds_read_b128 v[108:111], v68 offset:28672
	ds_read_b128 v[112:115], v68 offset:32768
	ds_read_b128 v[116:119], v68 offset:36864
	ds_read_b128 v[120:123], v68 offset:40960
	ds_read_b128 v[124:127], v68 offset:45056
	ds_read_b128 v[128:131], v68 offset:49152
	ds_read_b128 v[132:135], v68 offset:53248
	ds_read_b128 v[136:139], v68 offset:57344
	ds_read_b128 v[140:143], v68 offset:61440
	s_add_i32 s10, s10, 16
	s_waitcnt lgkmcnt(14)
	v_mov_b32_e32 v68, v83
	v_mov_b32_e32 v72, v87
	s_waitcnt lgkmcnt(13)
	v_mov_b32_e32 v156, v91
	s_waitcnt lgkmcnt(12)
	v_mov_b32_e32 v158, v95
	s_waitcnt lgkmcnt(11)
	v_mov_b32_e32 v160, v99
	s_waitcnt lgkmcnt(10)
	v_mov_b32_e32 v162, v103
	s_waitcnt lgkmcnt(9)
	v_mov_b32_e32 v164, v107
	s_waitcnt lgkmcnt(8)
	v_mov_b32_e32 v166, v111
	s_waitcnt lgkmcnt(7)
	v_mov_b32_e32 v168, v115
	s_waitcnt lgkmcnt(6)
	v_mov_b32_e32 v170, v119
	s_waitcnt lgkmcnt(5)
	v_mov_b32_e32 v172, v123
	s_waitcnt lgkmcnt(4)
	v_mov_b32_e32 v174, v127
	s_waitcnt lgkmcnt(3)
	v_mov_b32_e32 v176, v131
	s_waitcnt lgkmcnt(2)
	v_mov_b32_e32 v178, v135
	s_waitcnt lgkmcnt(1)
	v_mov_b32_e32 v180, v139
	s_waitcnt lgkmcnt(0)
	v_mov_b32_e32 v182, v143
	s_waitcnt vmcnt(7)
	v_pk_fma_f32 v[64:65], v[202:203], v[80:81], v[64:65] op_sel_hi:[1,0,1]
	v_pk_fma_f32 v[62:63], v[200:201], v[80:81], v[62:63] op_sel_hi:[1,0,1]
	v_pk_fma_f32 v[60:61], v[202:203], v[84:85], v[60:61] op_sel_hi:[1,0,1]
	v_pk_fma_f32 v[58:59], v[200:201], v[84:85], v[58:59] op_sel_hi:[1,0,1]
	v_pk_fma_f32 v[56:57], v[202:203], v[88:89], v[56:57] op_sel_hi:[1,0,1]
	v_pk_fma_f32 v[54:55], v[200:201], v[88:89], v[54:55] op_sel_hi:[1,0,1]
	v_pk_fma_f32 v[52:53], v[202:203], v[92:93], v[52:53] op_sel_hi:[1,0,1]
	v_pk_fma_f32 v[50:51], v[200:201], v[92:93], v[50:51] op_sel_hi:[1,0,1]
	v_pk_fma_f32 v[48:49], v[202:203], v[96:97], v[48:49] op_sel_hi:[1,0,1]
	v_pk_fma_f32 v[46:47], v[200:201], v[96:97], v[46:47] op_sel_hi:[1,0,1]
	v_pk_fma_f32 v[44:45], v[202:203], v[100:101], v[44:45] op_sel_hi:[1,0,1]
	v_pk_fma_f32 v[42:43], v[200:201], v[100:101], v[42:43] op_sel_hi:[1,0,1]
	v_pk_fma_f32 v[40:41], v[202:203], v[104:105], v[40:41] op_sel_hi:[1,0,1]
	v_pk_fma_f32 v[38:39], v[200:201], v[104:105], v[38:39] op_sel_hi:[1,0,1]
	v_pk_fma_f32 v[36:37], v[202:203], v[108:109], v[36:37] op_sel_hi:[1,0,1]
	v_pk_fma_f32 v[34:35], v[200:201], v[108:109], v[34:35] op_sel_hi:[1,0,1]
	v_pk_fma_f32 v[32:33], v[202:203], v[112:113], v[32:33] op_sel_hi:[1,0,1]
	v_pk_fma_f32 v[30:31], v[200:201], v[112:113], v[30:31] op_sel_hi:[1,0,1]
	v_pk_fma_f32 v[28:29], v[202:203], v[116:117], v[28:29] op_sel_hi:[1,0,1]
	v_pk_fma_f32 v[26:27], v[200:201], v[116:117], v[26:27] op_sel_hi:[1,0,1]
	v_pk_fma_f32 v[24:25], v[202:203], v[120:121], v[24:25] op_sel_hi:[1,0,1]
	v_pk_fma_f32 v[22:23], v[200:201], v[120:121], v[22:23] op_sel_hi:[1,0,1]
	v_pk_fma_f32 v[20:21], v[202:203], v[124:125], v[20:21] op_sel_hi:[1,0,1]
	v_pk_fma_f32 v[18:19], v[200:201], v[124:125], v[18:19] op_sel_hi:[1,0,1]
	v_pk_fma_f32 v[16:17], v[202:203], v[128:129], v[16:17] op_sel_hi:[1,0,1]
	v_pk_fma_f32 v[14:15], v[200:201], v[128:129], v[14:15] op_sel_hi:[1,0,1]
	v_pk_fma_f32 v[12:13], v[202:203], v[132:133], v[12:13] op_sel_hi:[1,0,1]
	v_pk_fma_f32 v[10:11], v[200:201], v[132:133], v[10:11] op_sel_hi:[1,0,1]
	v_pk_fma_f32 v[8:9], v[202:203], v[136:137], v[8:9] op_sel_hi:[1,0,1]
	v_pk_fma_f32 v[6:7], v[200:201], v[136:137], v[6:7] op_sel_hi:[1,0,1]
	v_pk_fma_f32 v[4:5], v[202:203], v[140:141], v[4:5] op_sel_hi:[1,0,1]
	v_pk_fma_f32 v[2:3], v[200:201], v[140:141], v[2:3] op_sel_hi:[1,0,1]
	s_waitcnt vmcnt(6)
	v_pk_fma_f32 v[62:63], v[204:205], v[80:81], v[62:63] op_sel:[0,1,0]
	v_pk_fma_f32 v[64:65], v[206:207], v[80:81], v[64:65] op_sel:[0,1,0]
	v_pk_fma_f32 v[58:59], v[204:205], v[84:85], v[58:59] op_sel:[0,1,0]
	v_pk_fma_f32 v[60:61], v[206:207], v[84:85], v[60:61] op_sel:[0,1,0]
	v_pk_fma_f32 v[54:55], v[204:205], v[88:89], v[54:55] op_sel:[0,1,0]
	v_pk_fma_f32 v[56:57], v[206:207], v[88:89], v[56:57] op_sel:[0,1,0]
	v_pk_fma_f32 v[50:51], v[204:205], v[92:93], v[50:51] op_sel:[0,1,0]
	v_pk_fma_f32 v[52:53], v[206:207], v[92:93], v[52:53] op_sel:[0,1,0]
	v_pk_fma_f32 v[46:47], v[204:205], v[96:97], v[46:47] op_sel:[0,1,0]
	v_pk_fma_f32 v[48:49], v[206:207], v[96:97], v[48:49] op_sel:[0,1,0]
	v_pk_fma_f32 v[42:43], v[204:205], v[100:101], v[42:43] op_sel:[0,1,0]
	v_pk_fma_f32 v[44:45], v[206:207], v[100:101], v[44:45] op_sel:[0,1,0]
	v_pk_fma_f32 v[38:39], v[204:205], v[104:105], v[38:39] op_sel:[0,1,0]
	v_pk_fma_f32 v[40:41], v[206:207], v[104:105], v[40:41] op_sel:[0,1,0]
	v_pk_fma_f32 v[34:35], v[204:205], v[108:109], v[34:35] op_sel:[0,1,0]
	v_pk_fma_f32 v[36:37], v[206:207], v[108:109], v[36:37] op_sel:[0,1,0]
	v_pk_fma_f32 v[30:31], v[204:205], v[112:113], v[30:31] op_sel:[0,1,0]
	v_pk_fma_f32 v[32:33], v[206:207], v[112:113], v[32:33] op_sel:[0,1,0]
	v_pk_fma_f32 v[26:27], v[204:205], v[116:117], v[26:27] op_sel:[0,1,0]
	v_pk_fma_f32 v[28:29], v[206:207], v[116:117], v[28:29] op_sel:[0,1,0]
	v_pk_fma_f32 v[22:23], v[204:205], v[120:121], v[22:23] op_sel:[0,1,0]
	v_pk_fma_f32 v[24:25], v[206:207], v[120:121], v[24:25] op_sel:[0,1,0]
	v_pk_fma_f32 v[18:19], v[204:205], v[124:125], v[18:19] op_sel:[0,1,0]
	v_pk_fma_f32 v[20:21], v[206:207], v[124:125], v[20:21] op_sel:[0,1,0]
	v_pk_fma_f32 v[14:15], v[204:205], v[128:129], v[14:15] op_sel:[0,1,0]
	v_pk_fma_f32 v[16:17], v[206:207], v[128:129], v[16:17] op_sel:[0,1,0]
	v_pk_fma_f32 v[10:11], v[204:205], v[132:133], v[10:11] op_sel:[0,1,0]
	v_pk_fma_f32 v[12:13], v[206:207], v[132:133], v[12:13] op_sel:[0,1,0]
	v_pk_fma_f32 v[6:7], v[204:205], v[136:137], v[6:7] op_sel:[0,1,0]
	v_pk_fma_f32 v[8:9], v[206:207], v[136:137], v[8:9] op_sel:[0,1,0]
	v_pk_fma_f32 v[2:3], v[204:205], v[140:141], v[2:3] op_sel:[0,1,0]
	v_pk_fma_f32 v[4:5], v[206:207], v[140:141], v[4:5] op_sel:[0,1,0]
	s_waitcnt vmcnt(5)
	v_pk_fma_f32 v[64:65], v[210:211], v[82:83], v[64:65] op_sel_hi:[1,0,1]
	v_pk_fma_f32 v[62:63], v[208:209], v[82:83], v[62:63] op_sel_hi:[1,0,1]
	v_pk_fma_f32 v[60:61], v[210:211], v[86:87], v[60:61] op_sel_hi:[1,0,1]
	v_pk_fma_f32 v[58:59], v[208:209], v[86:87], v[58:59] op_sel_hi:[1,0,1]
	v_pk_fma_f32 v[56:57], v[210:211], v[90:91], v[56:57] op_sel_hi:[1,0,1]
	v_pk_fma_f32 v[54:55], v[208:209], v[90:91], v[54:55] op_sel_hi:[1,0,1]
	v_pk_fma_f32 v[52:53], v[210:211], v[94:95], v[52:53] op_sel_hi:[1,0,1]
	v_pk_fma_f32 v[50:51], v[208:209], v[94:95], v[50:51] op_sel_hi:[1,0,1]
	v_pk_fma_f32 v[48:49], v[210:211], v[98:99], v[48:49] op_sel_hi:[1,0,1]
	v_pk_fma_f32 v[46:47], v[208:209], v[98:99], v[46:47] op_sel_hi:[1,0,1]
	v_pk_fma_f32 v[44:45], v[210:211], v[102:103], v[44:45] op_sel_hi:[1,0,1]
	v_pk_fma_f32 v[42:43], v[208:209], v[102:103], v[42:43] op_sel_hi:[1,0,1]
	v_pk_fma_f32 v[40:41], v[210:211], v[106:107], v[40:41] op_sel_hi:[1,0,1]
	v_pk_fma_f32 v[38:39], v[208:209], v[106:107], v[38:39] op_sel_hi:[1,0,1]
	v_pk_fma_f32 v[36:37], v[210:211], v[110:111], v[36:37] op_sel_hi:[1,0,1]
	v_pk_fma_f32 v[34:35], v[208:209], v[110:111], v[34:35] op_sel_hi:[1,0,1]
	v_pk_fma_f32 v[32:33], v[210:211], v[114:115], v[32:33] op_sel_hi:[1,0,1]
	v_pk_fma_f32 v[30:31], v[208:209], v[114:115], v[30:31] op_sel_hi:[1,0,1]
	v_pk_fma_f32 v[28:29], v[210:211], v[118:119], v[28:29] op_sel_hi:[1,0,1]
	v_pk_fma_f32 v[26:27], v[208:209], v[118:119], v[26:27] op_sel_hi:[1,0,1]
	v_pk_fma_f32 v[24:25], v[210:211], v[122:123], v[24:25] op_sel_hi:[1,0,1]
	v_pk_fma_f32 v[22:23], v[208:209], v[122:123], v[22:23] op_sel_hi:[1,0,1]
	v_pk_fma_f32 v[20:21], v[210:211], v[126:127], v[20:21] op_sel_hi:[1,0,1]
	v_pk_fma_f32 v[18:19], v[208:209], v[126:127], v[18:19] op_sel_hi:[1,0,1]
	v_pk_fma_f32 v[16:17], v[210:211], v[130:131], v[16:17] op_sel_hi:[1,0,1]
	v_pk_fma_f32 v[14:15], v[208:209], v[130:131], v[14:15] op_sel_hi:[1,0,1]
	v_pk_fma_f32 v[12:13], v[210:211], v[134:135], v[12:13] op_sel_hi:[1,0,1]
	v_pk_fma_f32 v[10:11], v[208:209], v[134:135], v[10:11] op_sel_hi:[1,0,1]
	v_pk_fma_f32 v[8:9], v[210:211], v[138:139], v[8:9] op_sel_hi:[1,0,1]
	v_pk_fma_f32 v[6:7], v[208:209], v[138:139], v[6:7] op_sel_hi:[1,0,1]
	v_pk_fma_f32 v[4:5], v[210:211], v[142:143], v[4:5] op_sel_hi:[1,0,1]
	v_pk_fma_f32 v[2:3], v[208:209], v[142:143], v[2:3] op_sel_hi:[1,0,1]
	s_waitcnt vmcnt(4)
	v_pk_fma_f32 v[64:65], v[214:215], v[68:69], v[64:65] op_sel_hi:[1,0,1]
	v_pk_fma_f32 v[62:63], v[212:213], v[68:69], v[62:63] op_sel_hi:[1,0,1]
	v_pk_fma_f32 v[60:61], v[214:215], v[72:73], v[60:61] op_sel_hi:[1,0,1]
	v_pk_fma_f32 v[58:59], v[212:213], v[72:73], v[58:59] op_sel_hi:[1,0,1]
	v_pk_fma_f32 v[56:57], v[214:215], v[156:157], v[56:57] op_sel_hi:[1,0,1]
	v_pk_fma_f32 v[54:55], v[212:213], v[156:157], v[54:55] op_sel_hi:[1,0,1]
	v_pk_fma_f32 v[52:53], v[214:215], v[158:159], v[52:53] op_sel_hi:[1,0,1]
	v_pk_fma_f32 v[50:51], v[212:213], v[158:159], v[50:51] op_sel_hi:[1,0,1]
	v_pk_fma_f32 v[48:49], v[214:215], v[160:161], v[48:49] op_sel_hi:[1,0,1]
	v_pk_fma_f32 v[46:47], v[212:213], v[160:161], v[46:47] op_sel_hi:[1,0,1]
	v_pk_fma_f32 v[44:45], v[214:215], v[162:163], v[44:45] op_sel_hi:[1,0,1]
	v_pk_fma_f32 v[42:43], v[212:213], v[162:163], v[42:43] op_sel_hi:[1,0,1]
	v_pk_fma_f32 v[40:41], v[214:215], v[164:165], v[40:41] op_sel_hi:[1,0,1]
	v_pk_fma_f32 v[38:39], v[212:213], v[164:165], v[38:39] op_sel_hi:[1,0,1]
	v_pk_fma_f32 v[36:37], v[214:215], v[166:167], v[36:37] op_sel_hi:[1,0,1]
	v_pk_fma_f32 v[34:35], v[212:213], v[166:167], v[34:35] op_sel_hi:[1,0,1]
	v_pk_fma_f32 v[32:33], v[214:215], v[168:169], v[32:33] op_sel_hi:[1,0,1]
	v_pk_fma_f32 v[30:31], v[212:213], v[168:169], v[30:31] op_sel_hi:[1,0,1]
	v_pk_fma_f32 v[28:29], v[214:215], v[170:171], v[28:29] op_sel_hi:[1,0,1]
	v_pk_fma_f32 v[26:27], v[212:213], v[170:171], v[26:27] op_sel_hi:[1,0,1]
	v_pk_fma_f32 v[24:25], v[214:215], v[172:173], v[24:25] op_sel_hi:[1,0,1]
	v_pk_fma_f32 v[22:23], v[212:213], v[172:173], v[22:23] op_sel_hi:[1,0,1]
	v_pk_fma_f32 v[20:21], v[214:215], v[174:175], v[20:21] op_sel_hi:[1,0,1]
	v_pk_fma_f32 v[18:19], v[212:213], v[174:175], v[18:19] op_sel_hi:[1,0,1]
	v_pk_fma_f32 v[16:17], v[214:215], v[176:177], v[16:17] op_sel_hi:[1,0,1]
	v_pk_fma_f32 v[14:15], v[212:213], v[176:177], v[14:15] op_sel_hi:[1,0,1]
	v_pk_fma_f32 v[12:13], v[214:215], v[178:179], v[12:13] op_sel_hi:[1,0,1]
	v_pk_fma_f32 v[10:11], v[212:213], v[178:179], v[10:11] op_sel_hi:[1,0,1]
	v_pk_fma_f32 v[8:9], v[214:215], v[180:181], v[8:9] op_sel_hi:[1,0,1]
	v_pk_fma_f32 v[6:7], v[212:213], v[180:181], v[6:7] op_sel_hi:[1,0,1]
	v_pk_fma_f32 v[4:5], v[214:215], v[182:183], v[4:5] op_sel_hi:[1,0,1]
	v_pk_fma_f32 v[2:3], v[212:213], v[182:183], v[2:3] op_sel_hi:[1,0,1]
	v_mov_b32_e32 v68, s10
	ds_read_b128 v[80:83], v68
	ds_read_b128 v[84:87], v68 offset:4096
	ds_read_b128 v[88:91], v68 offset:8192
	ds_read_b128 v[92:95], v68 offset:12288
	ds_read_b128 v[96:99], v68 offset:16384
	ds_read_b128 v[100:103], v68 offset:20480
	ds_read_b128 v[104:107], v68 offset:24576
	ds_read_b128 v[108:111], v68 offset:28672
	ds_read_b128 v[112:115], v68 offset:32768
	ds_read_b128 v[116:119], v68 offset:36864
	ds_read_b128 v[120:123], v68 offset:40960
	ds_read_b128 v[124:127], v68 offset:45056
	ds_read_b128 v[128:131], v68 offset:49152
	ds_read_b128 v[132:135], v68 offset:53248
	ds_read_b128 v[136:139], v68 offset:57344
	ds_read_b128 v[140:143], v68 offset:61440
	s_add_i32 s10, s10, 16
	s_waitcnt lgkmcnt(14)
	v_mov_b32_e32 v68, v83
	v_mov_b32_e32 v72, v87
	s_waitcnt lgkmcnt(13)
	v_mov_b32_e32 v156, v91
	s_waitcnt lgkmcnt(12)
	v_mov_b32_e32 v158, v95
	s_waitcnt lgkmcnt(11)
	v_mov_b32_e32 v160, v99
	s_waitcnt lgkmcnt(10)
	v_mov_b32_e32 v162, v103
	s_waitcnt lgkmcnt(9)
	v_mov_b32_e32 v164, v107
	s_waitcnt lgkmcnt(8)
	v_mov_b32_e32 v166, v111
	s_waitcnt lgkmcnt(7)
	v_mov_b32_e32 v168, v115
	s_waitcnt lgkmcnt(6)
	v_mov_b32_e32 v170, v119
	s_waitcnt lgkmcnt(5)
	v_mov_b32_e32 v172, v123
	s_waitcnt lgkmcnt(4)
	v_mov_b32_e32 v174, v127
	s_waitcnt lgkmcnt(3)
	v_mov_b32_e32 v176, v131
	s_waitcnt lgkmcnt(2)
	v_mov_b32_e32 v178, v135
	s_waitcnt lgkmcnt(1)
	v_mov_b32_e32 v180, v139
	s_waitcnt lgkmcnt(0)
	v_mov_b32_e32 v182, v143
	s_waitcnt vmcnt(3)
	v_pk_fma_f32 v[64:65], v[218:219], v[80:81], v[64:65] op_sel_hi:[1,0,1]
	v_pk_fma_f32 v[62:63], v[216:217], v[80:81], v[62:63] op_sel_hi:[1,0,1]
	v_pk_fma_f32 v[60:61], v[218:219], v[84:85], v[60:61] op_sel_hi:[1,0,1]
	v_pk_fma_f32 v[58:59], v[216:217], v[84:85], v[58:59] op_sel_hi:[1,0,1]
	v_pk_fma_f32 v[56:57], v[218:219], v[88:89], v[56:57] op_sel_hi:[1,0,1]
	v_pk_fma_f32 v[54:55], v[216:217], v[88:89], v[54:55] op_sel_hi:[1,0,1]
	v_pk_fma_f32 v[52:53], v[218:219], v[92:93], v[52:53] op_sel_hi:[1,0,1]
	v_pk_fma_f32 v[50:51], v[216:217], v[92:93], v[50:51] op_sel_hi:[1,0,1]
	v_pk_fma_f32 v[48:49], v[218:219], v[96:97], v[48:49] op_sel_hi:[1,0,1]
	v_pk_fma_f32 v[46:47], v[216:217], v[96:97], v[46:47] op_sel_hi:[1,0,1]
	v_pk_fma_f32 v[44:45], v[218:219], v[100:101], v[44:45] op_sel_hi:[1,0,1]
	v_pk_fma_f32 v[42:43], v[216:217], v[100:101], v[42:43] op_sel_hi:[1,0,1]
	v_pk_fma_f32 v[40:41], v[218:219], v[104:105], v[40:41] op_sel_hi:[1,0,1]
	v_pk_fma_f32 v[38:39], v[216:217], v[104:105], v[38:39] op_sel_hi:[1,0,1]
	v_pk_fma_f32 v[36:37], v[218:219], v[108:109], v[36:37] op_sel_hi:[1,0,1]
	v_pk_fma_f32 v[34:35], v[216:217], v[108:109], v[34:35] op_sel_hi:[1,0,1]
	v_pk_fma_f32 v[32:33], v[218:219], v[112:113], v[32:33] op_sel_hi:[1,0,1]
	v_pk_fma_f32 v[30:31], v[216:217], v[112:113], v[30:31] op_sel_hi:[1,0,1]
	v_pk_fma_f32 v[28:29], v[218:219], v[116:117], v[28:29] op_sel_hi:[1,0,1]
	v_pk_fma_f32 v[26:27], v[216:217], v[116:117], v[26:27] op_sel_hi:[1,0,1]
	v_pk_fma_f32 v[24:25], v[218:219], v[120:121], v[24:25] op_sel_hi:[1,0,1]
	v_pk_fma_f32 v[22:23], v[216:217], v[120:121], v[22:23] op_sel_hi:[1,0,1]
	v_pk_fma_f32 v[20:21], v[218:219], v[124:125], v[20:21] op_sel_hi:[1,0,1]
	v_pk_fma_f32 v[18:19], v[216:217], v[124:125], v[18:19] op_sel_hi:[1,0,1]
	v_pk_fma_f32 v[16:17], v[218:219], v[128:129], v[16:17] op_sel_hi:[1,0,1]
	v_pk_fma_f32 v[14:15], v[216:217], v[128:129], v[14:15] op_sel_hi:[1,0,1]
	v_pk_fma_f32 v[12:13], v[218:219], v[132:133], v[12:13] op_sel_hi:[1,0,1]
	v_pk_fma_f32 v[10:11], v[216:217], v[132:133], v[10:11] op_sel_hi:[1,0,1]
	v_pk_fma_f32 v[8:9], v[218:219], v[136:137], v[8:9] op_sel_hi:[1,0,1]
	v_pk_fma_f32 v[6:7], v[216:217], v[136:137], v[6:7] op_sel_hi:[1,0,1]
	v_pk_fma_f32 v[4:5], v[218:219], v[140:141], v[4:5] op_sel_hi:[1,0,1]
	v_pk_fma_f32 v[2:3], v[216:217], v[140:141], v[2:3] op_sel_hi:[1,0,1]
	s_waitcnt vmcnt(2)
	v_pk_fma_f32 v[62:63], v[220:221], v[80:81], v[62:63] op_sel:[0,1,0]
	v_pk_fma_f32 v[64:65], v[222:223], v[80:81], v[64:65] op_sel:[0,1,0]
	v_pk_fma_f32 v[58:59], v[220:221], v[84:85], v[58:59] op_sel:[0,1,0]
	v_pk_fma_f32 v[60:61], v[222:223], v[84:85], v[60:61] op_sel:[0,1,0]
	v_pk_fma_f32 v[54:55], v[220:221], v[88:89], v[54:55] op_sel:[0,1,0]
	v_pk_fma_f32 v[56:57], v[222:223], v[88:89], v[56:57] op_sel:[0,1,0]
	v_pk_fma_f32 v[50:51], v[220:221], v[92:93], v[50:51] op_sel:[0,1,0]
	v_pk_fma_f32 v[52:53], v[222:223], v[92:93], v[52:53] op_sel:[0,1,0]
	v_pk_fma_f32 v[46:47], v[220:221], v[96:97], v[46:47] op_sel:[0,1,0]
	v_pk_fma_f32 v[48:49], v[222:223], v[96:97], v[48:49] op_sel:[0,1,0]
	v_pk_fma_f32 v[42:43], v[220:221], v[100:101], v[42:43] op_sel:[0,1,0]
	v_pk_fma_f32 v[44:45], v[222:223], v[100:101], v[44:45] op_sel:[0,1,0]
	v_pk_fma_f32 v[38:39], v[220:221], v[104:105], v[38:39] op_sel:[0,1,0]
	v_pk_fma_f32 v[40:41], v[222:223], v[104:105], v[40:41] op_sel:[0,1,0]
	v_pk_fma_f32 v[34:35], v[220:221], v[108:109], v[34:35] op_sel:[0,1,0]
	v_pk_fma_f32 v[36:37], v[222:223], v[108:109], v[36:37] op_sel:[0,1,0]
	v_pk_fma_f32 v[30:31], v[220:221], v[112:113], v[30:31] op_sel:[0,1,0]
	v_pk_fma_f32 v[32:33], v[222:223], v[112:113], v[32:33] op_sel:[0,1,0]
	v_pk_fma_f32 v[26:27], v[220:221], v[116:117], v[26:27] op_sel:[0,1,0]
	v_pk_fma_f32 v[28:29], v[222:223], v[116:117], v[28:29] op_sel:[0,1,0]
	v_pk_fma_f32 v[22:23], v[220:221], v[120:121], v[22:23] op_sel:[0,1,0]
	v_pk_fma_f32 v[24:25], v[222:223], v[120:121], v[24:25] op_sel:[0,1,0]
	v_pk_fma_f32 v[18:19], v[220:221], v[124:125], v[18:19] op_sel:[0,1,0]
	v_pk_fma_f32 v[20:21], v[222:223], v[124:125], v[20:21] op_sel:[0,1,0]
	v_pk_fma_f32 v[14:15], v[220:221], v[128:129], v[14:15] op_sel:[0,1,0]
	v_pk_fma_f32 v[16:17], v[222:223], v[128:129], v[16:17] op_sel:[0,1,0]
	v_pk_fma_f32 v[10:11], v[220:221], v[132:133], v[10:11] op_sel:[0,1,0]
	v_pk_fma_f32 v[12:13], v[222:223], v[132:133], v[12:13] op_sel:[0,1,0]
	v_pk_fma_f32 v[6:7], v[220:221], v[136:137], v[6:7] op_sel:[0,1,0]
	v_pk_fma_f32 v[8:9], v[222:223], v[136:137], v[8:9] op_sel:[0,1,0]
	v_pk_fma_f32 v[2:3], v[220:221], v[140:141], v[2:3] op_sel:[0,1,0]
	v_pk_fma_f32 v[4:5], v[222:223], v[140:141], v[4:5] op_sel:[0,1,0]
	s_waitcnt vmcnt(1)
	v_pk_fma_f32 v[64:65], v[226:227], v[82:83], v[64:65] op_sel_hi:[1,0,1]
	v_pk_fma_f32 v[62:63], v[224:225], v[82:83], v[62:63] op_sel_hi:[1,0,1]
	v_pk_fma_f32 v[60:61], v[226:227], v[86:87], v[60:61] op_sel_hi:[1,0,1]
	v_pk_fma_f32 v[58:59], v[224:225], v[86:87], v[58:59] op_sel_hi:[1,0,1]
	v_pk_fma_f32 v[56:57], v[226:227], v[90:91], v[56:57] op_sel_hi:[1,0,1]
	v_pk_fma_f32 v[54:55], v[224:225], v[90:91], v[54:55] op_sel_hi:[1,0,1]
	v_pk_fma_f32 v[52:53], v[226:227], v[94:95], v[52:53] op_sel_hi:[1,0,1]
	v_pk_fma_f32 v[50:51], v[224:225], v[94:95], v[50:51] op_sel_hi:[1,0,1]
	v_pk_fma_f32 v[48:49], v[226:227], v[98:99], v[48:49] op_sel_hi:[1,0,1]
	v_pk_fma_f32 v[46:47], v[224:225], v[98:99], v[46:47] op_sel_hi:[1,0,1]
	v_pk_fma_f32 v[44:45], v[226:227], v[102:103], v[44:45] op_sel_hi:[1,0,1]
	v_pk_fma_f32 v[42:43], v[224:225], v[102:103], v[42:43] op_sel_hi:[1,0,1]
	v_pk_fma_f32 v[40:41], v[226:227], v[106:107], v[40:41] op_sel_hi:[1,0,1]
	v_pk_fma_f32 v[38:39], v[224:225], v[106:107], v[38:39] op_sel_hi:[1,0,1]
	v_pk_fma_f32 v[36:37], v[226:227], v[110:111], v[36:37] op_sel_hi:[1,0,1]
	v_pk_fma_f32 v[34:35], v[224:225], v[110:111], v[34:35] op_sel_hi:[1,0,1]
	v_pk_fma_f32 v[32:33], v[226:227], v[114:115], v[32:33] op_sel_hi:[1,0,1]
	v_pk_fma_f32 v[30:31], v[224:225], v[114:115], v[30:31] op_sel_hi:[1,0,1]
	v_pk_fma_f32 v[28:29], v[226:227], v[118:119], v[28:29] op_sel_hi:[1,0,1]
	v_pk_fma_f32 v[26:27], v[224:225], v[118:119], v[26:27] op_sel_hi:[1,0,1]
	v_pk_fma_f32 v[24:25], v[226:227], v[122:123], v[24:25] op_sel_hi:[1,0,1]
	v_pk_fma_f32 v[22:23], v[224:225], v[122:123], v[22:23] op_sel_hi:[1,0,1]
	v_pk_fma_f32 v[20:21], v[226:227], v[126:127], v[20:21] op_sel_hi:[1,0,1]
	v_pk_fma_f32 v[18:19], v[224:225], v[126:127], v[18:19] op_sel_hi:[1,0,1]
	v_pk_fma_f32 v[16:17], v[226:227], v[130:131], v[16:17] op_sel_hi:[1,0,1]
	v_pk_fma_f32 v[14:15], v[224:225], v[130:131], v[14:15] op_sel_hi:[1,0,1]
	v_pk_fma_f32 v[12:13], v[226:227], v[134:135], v[12:13] op_sel_hi:[1,0,1]
	v_pk_fma_f32 v[10:11], v[224:225], v[134:135], v[10:11] op_sel_hi:[1,0,1]
	v_pk_fma_f32 v[8:9], v[226:227], v[138:139], v[8:9] op_sel_hi:[1,0,1]
	v_pk_fma_f32 v[6:7], v[224:225], v[138:139], v[6:7] op_sel_hi:[1,0,1]
	v_pk_fma_f32 v[4:5], v[226:227], v[142:143], v[4:5] op_sel_hi:[1,0,1]
	v_pk_fma_f32 v[2:3], v[224:225], v[142:143], v[2:3] op_sel_hi:[1,0,1]
	s_waitcnt vmcnt(0)
	v_pk_fma_f32 v[64:65], v[230:231], v[68:69], v[64:65] op_sel_hi:[1,0,1]
	v_pk_fma_f32 v[62:63], v[228:229], v[68:69], v[62:63] op_sel_hi:[1,0,1]
	v_pk_fma_f32 v[60:61], v[230:231], v[72:73], v[60:61] op_sel_hi:[1,0,1]
	v_pk_fma_f32 v[58:59], v[228:229], v[72:73], v[58:59] op_sel_hi:[1,0,1]
	v_pk_fma_f32 v[56:57], v[230:231], v[156:157], v[56:57] op_sel_hi:[1,0,1]
	v_pk_fma_f32 v[54:55], v[228:229], v[156:157], v[54:55] op_sel_hi:[1,0,1]
	v_pk_fma_f32 v[52:53], v[230:231], v[158:159], v[52:53] op_sel_hi:[1,0,1]
	v_pk_fma_f32 v[50:51], v[228:229], v[158:159], v[50:51] op_sel_hi:[1,0,1]
	v_pk_fma_f32 v[48:49], v[230:231], v[160:161], v[48:49] op_sel_hi:[1,0,1]
	v_pk_fma_f32 v[46:47], v[228:229], v[160:161], v[46:47] op_sel_hi:[1,0,1]
	v_pk_fma_f32 v[44:45], v[230:231], v[162:163], v[44:45] op_sel_hi:[1,0,1]
	v_pk_fma_f32 v[42:43], v[228:229], v[162:163], v[42:43] op_sel_hi:[1,0,1]
	v_pk_fma_f32 v[40:41], v[230:231], v[164:165], v[40:41] op_sel_hi:[1,0,1]
	v_pk_fma_f32 v[38:39], v[228:229], v[164:165], v[38:39] op_sel_hi:[1,0,1]
	v_pk_fma_f32 v[36:37], v[230:231], v[166:167], v[36:37] op_sel_hi:[1,0,1]
	v_pk_fma_f32 v[34:35], v[228:229], v[166:167], v[34:35] op_sel_hi:[1,0,1]
	v_pk_fma_f32 v[32:33], v[230:231], v[168:169], v[32:33] op_sel_hi:[1,0,1]
	v_pk_fma_f32 v[30:31], v[228:229], v[168:169], v[30:31] op_sel_hi:[1,0,1]
	v_pk_fma_f32 v[28:29], v[230:231], v[170:171], v[28:29] op_sel_hi:[1,0,1]
	v_pk_fma_f32 v[26:27], v[228:229], v[170:171], v[26:27] op_sel_hi:[1,0,1]
	v_pk_fma_f32 v[24:25], v[230:231], v[172:173], v[24:25] op_sel_hi:[1,0,1]
	v_pk_fma_f32 v[22:23], v[228:229], v[172:173], v[22:23] op_sel_hi:[1,0,1]
	v_pk_fma_f32 v[20:21], v[230:231], v[174:175], v[20:21] op_sel_hi:[1,0,1]
	v_pk_fma_f32 v[18:19], v[228:229], v[174:175], v[18:19] op_sel_hi:[1,0,1]
	v_pk_fma_f32 v[16:17], v[230:231], v[176:177], v[16:17] op_sel_hi:[1,0,1]
	v_pk_fma_f32 v[14:15], v[228:229], v[176:177], v[14:15] op_sel_hi:[1,0,1]
	v_pk_fma_f32 v[12:13], v[230:231], v[178:179], v[12:13] op_sel_hi:[1,0,1]
	v_pk_fma_f32 v[10:11], v[228:229], v[178:179], v[10:11] op_sel_hi:[1,0,1]
	v_pk_fma_f32 v[8:9], v[230:231], v[180:181], v[8:9] op_sel_hi:[1,0,1]
	v_pk_fma_f32 v[6:7], v[228:229], v[180:181], v[6:7] op_sel_hi:[1,0,1]
	v_pk_fma_f32 v[4:5], v[230:231], v[182:183], v[4:5] op_sel_hi:[1,0,1]
	v_pk_fma_f32 v[2:3], v[228:229], v[182:183], v[2:3] op_sel_hi:[1,0,1]
	s_and_saveexec_b64 s[0:1], vcc
	s_cbranch_execz .LBB0_14
	ds_write_b128 v75, v[62:65]
	ds_write_b128 v75, v[58:61] offset:576
	ds_write_b128 v75, v[54:57] offset:1152
	ds_write_b128 v75, v[50:53] offset:1728
	ds_write_b128 v75, v[46:49] offset:2304
	ds_write_b128 v75, v[42:45] offset:2880
	ds_write_b128 v75, v[38:41] offset:3456
	ds_write_b128 v75, v[34:37] offset:4032
	ds_write_b128 v75, v[30:33] offset:4608
	ds_write_b128 v75, v[26:29] offset:5184
	ds_write_b128 v75, v[22:25] offset:5760
	ds_write_b128 v75, v[18:21] offset:6336
	ds_write_b128 v75, v[14:17] offset:6912
	ds_write_b128 v75, v[10:13] offset:7488
	ds_write_b128 v75, v[6:9] offset:8064
	ds_write_b128 v75, v[2:5] offset:8640
